# deleted the 42 duplicate compiler s_waitcnt lgkmcnt(0) after s_setprio 1 in the 7 GEMM K-loops, nop-compensated after each back-branch so all code addresses stay
# speedup vs baseline: 1.0350x; 1.0087x over previous
.LBB0_47:
	s_add_u32 s24, s22, 0x100
	s_addc_u32 s25, s23, 0
	s_add_i32 s46, 0, 0x10000
	v_add_u32_e32 v142, s46, v191
	ds_read_b128 v[130:133], v142
	ds_read_b128 v[134:137], v142 offset:1024
	ds_read_b128 v[138:141], v142 offset:2048
	ds_read_b128 v[142:145], v142 offset:3072
	s_cmp_eq_u32 s45, 28
	s_cselect_b32 s29, s17, s25
	s_cselect_b32 s28, s41, s24
	s_cselect_b32 s27, s15, s44
	s_cselect_b32 s26, s42, s43
	v_lshl_add_u64 v[194:195], s[22:23], 0, v[182:183]
	s_add_i32 m0, s30, 0xc000
	ds_read_b128 v[146:149], v212
	ds_read_b128 v[150:153], v212 offset:1024
	ds_read_b128 v[154:157], v212 offset:2048
	ds_read_b128 v[158:161], v212 offset:3072
	ds_read_b128 v[162:165], v212 offset:4096
	ds_read_b128 v[166:169], v212 offset:5120
	ds_read_b128 v[170:173], v212 offset:6144
	ds_read_b128 v[174:177], v212 offset:7168
	global_load_lds_dwordx4 v[194:195], off
	v_lshl_add_u64 v[194:195], s[22:23], 0, v[184:185]
	s_add_i32 m0, s30, 0xe000
	s_nop 0
	global_load_lds_dwordx4 v[194:195], off
	s_waitcnt lgkmcnt(8)
	s_barrier
	s_waitcnt lgkmcnt(0)
	s_setprio 1
	v_mfma_f32_16x16x32_bf16 v[126:129], v[130:133], v[146:149], v[126:129]
	v_mfma_f32_16x16x32_bf16 v[122:125], v[138:141], v[146:149], v[122:125]
	v_mfma_f32_16x16x32_bf16 v[110:113], v[130:133], v[154:157], v[110:113]
	v_mfma_f32_16x16x32_bf16 v[106:109], v[138:141], v[154:157], v[106:109]
	v_mfma_f32_16x16x32_bf16 v[94:97], v[130:133], v[162:165], v[94:97]
	v_mfma_f32_16x16x32_bf16 v[90:93], v[138:141], v[162:165], v[90:93]
	v_mfma_f32_16x16x32_bf16 v[78:81], v[130:133], v[170:173], v[78:81]
	v_mfma_f32_16x16x32_bf16 v[74:77], v[138:141], v[170:173], v[74:77]
	v_mfma_f32_16x16x32_bf16 v[126:129], v[134:137], v[150:153], v[126:129]
	v_mfma_f32_16x16x32_bf16 v[122:125], v[142:145], v[150:153], v[122:125]
	v_mfma_f32_16x16x32_bf16 v[110:113], v[134:137], v[158:161], v[110:113]
	v_mfma_f32_16x16x32_bf16 v[106:109], v[142:145], v[158:161], v[106:109]
	v_mfma_f32_16x16x32_bf16 v[94:97], v[134:137], v[166:169], v[94:97]
	v_mfma_f32_16x16x32_bf16 v[90:93], v[142:145], v[166:169], v[90:93]
	v_mfma_f32_16x16x32_bf16 v[78:81], v[134:137], v[174:177], v[78:81]
	v_mfma_f32_16x16x32_bf16 v[74:77], v[142:145], v[174:177], v[74:77]
	s_setprio 0
	s_barrier
	s_add_i32 s47, 0, 0x14000
	s_add_i32 s22, s46, s5
	v_add_u32_e32 v206, s47, v191
	v_lshl_add_u64 v[210:211], s[26:27], 0, v[180:181]
	s_mov_b32 m0, s22
	ds_read_b128 v[194:197], v206
	ds_read_b128 v[198:201], v206 offset:1024
	ds_read_b128 v[202:205], v206 offset:2048
	ds_read_b128 v[206:209], v206 offset:3072
	global_load_lds_dwordx4 v[210:211], off
	v_lshl_add_u64 v[220:221], s[26:27], 0, v[178:179]
	s_add_i32 m0, s22, 0x2000
	s_nop 0
	global_load_lds_dwordx4 v[220:221], off
	s_barrier
	s_waitcnt lgkmcnt(0)
	s_setprio 1
	v_mfma_f32_16x16x32_bf16 v[118:121], v[194:197], v[146:149], v[118:121]
	v_mfma_f32_16x16x32_bf16 v[114:117], v[202:205], v[146:149], v[114:117]
	v_mfma_f32_16x16x32_bf16 v[102:105], v[194:197], v[154:157], v[102:105]
	v_mfma_f32_16x16x32_bf16 v[98:101], v[202:205], v[154:157], v[98:101]
	v_mfma_f32_16x16x32_bf16 v[86:89], v[194:197], v[162:165], v[86:89]
	v_mfma_f32_16x16x32_bf16 v[82:85], v[202:205], v[162:165], v[82:85]
	v_mfma_f32_16x16x32_bf16 v[70:73], v[194:197], v[170:173], v[70:73]
	v_mfma_f32_16x16x32_bf16 v[66:69], v[202:205], v[170:173], v[66:69]
	v_mfma_f32_16x16x32_bf16 v[118:121], v[198:201], v[150:153], v[118:121]
	v_mfma_f32_16x16x32_bf16 v[114:117], v[206:209], v[150:153], v[114:117]
	v_mfma_f32_16x16x32_bf16 v[102:105], v[198:201], v[158:161], v[102:105]
	v_mfma_f32_16x16x32_bf16 v[98:101], v[206:209], v[158:161], v[98:101]
	v_mfma_f32_16x16x32_bf16 v[86:89], v[198:201], v[166:169], v[86:89]
	v_mfma_f32_16x16x32_bf16 v[82:85], v[206:209], v[166:169], v[82:85]
	v_mfma_f32_16x16x32_bf16 v[70:73], v[198:201], v[174:177], v[70:73]
	v_mfma_f32_16x16x32_bf16 v[66:69], v[206:209], v[174:177], v[66:69]
	s_setprio 0
	s_mov_b32 m0, s30
	v_lshl_add_u64 v[222:223], s[28:29], 0, v[180:181]
	s_barrier
	ds_read_b128 v[146:149], v212 offset:16384
	ds_read_b128 v[150:153], v212 offset:17408
	ds_read_b128 v[154:157], v212 offset:18432
	ds_read_b128 v[158:161], v212 offset:19456
	ds_read_b128 v[162:165], v212 offset:20480
	ds_read_b128 v[166:169], v212 offset:21504
	ds_read_b128 v[170:173], v212 offset:22528
	ds_read_b128 v[174:177], v212 offset:23552
	global_load_lds_dwordx4 v[222:223], off
	v_lshl_add_u64 v[224:225], s[28:29], 0, v[178:179]
	s_mov_b32 m0, s31
	s_nop 0
	global_load_lds_dwordx4 v[224:225], off
	s_barrier
	s_waitcnt lgkmcnt(0)
	s_setprio 1
	v_mfma_f32_16x16x32_bf16 v[62:65], v[130:133], v[146:149], v[62:65]
	v_mfma_f32_16x16x32_bf16 v[58:61], v[138:141], v[146:149], v[58:61]
	v_mfma_f32_16x16x32_bf16 v[46:49], v[130:133], v[154:157], v[46:49]
	v_mfma_f32_16x16x32_bf16 v[42:45], v[138:141], v[154:157], v[42:45]
	v_mfma_f32_16x16x32_bf16 v[30:33], v[130:133], v[162:165], v[30:33]
	v_mfma_f32_16x16x32_bf16 v[26:29], v[138:141], v[162:165], v[26:29]
	v_mfma_f32_16x16x32_bf16 v[14:17], v[130:133], v[170:173], v[14:17]
	v_mfma_f32_16x16x32_bf16 v[10:13], v[138:141], v[170:173], v[10:13]
	v_mfma_f32_16x16x32_bf16 v[62:65], v[134:137], v[150:153], v[62:65]
	v_mfma_f32_16x16x32_bf16 v[58:61], v[142:145], v[150:153], v[58:61]
	v_mfma_f32_16x16x32_bf16 v[46:49], v[134:137], v[158:161], v[46:49]
	v_mfma_f32_16x16x32_bf16 v[42:45], v[142:145], v[158:161], v[42:45]
	v_mfma_f32_16x16x32_bf16 v[30:33], v[134:137], v[166:169], v[30:33]
	v_mfma_f32_16x16x32_bf16 v[26:29], v[142:145], v[166:169], v[26:29]
	v_mfma_f32_16x16x32_bf16 v[14:17], v[134:137], v[174:177], v[14:17]
	v_mfma_f32_16x16x32_bf16 v[10:13], v[142:145], v[174:177], v[10:13]
	s_setprio 0
	s_barrier
	s_add_u32 s22, s26, 0x80000
	s_addc_u32 s23, s27, 0
	s_add_i32 s46, s47, s5
	v_lshl_add_u64 v[130:131], s[22:23], 0, v[180:181]
	s_mov_b32 m0, s46
	s_nop 0
	global_load_lds_dwordx4 v[130:131], off
	v_lshl_add_u64 v[130:131], s[22:23], 0, v[178:179]
	s_add_i32 m0, s46, 0x2000
	s_nop 0
	global_load_lds_dwordx4 v[130:131], off
	s_waitcnt vmcnt(6)
	s_barrier
	s_setprio 1
	v_mfma_f32_16x16x32_bf16 v[54:57], v[194:197], v[146:149], v[54:57]
	v_mfma_f32_16x16x32_bf16 v[50:53], v[202:205], v[146:149], v[50:53]
	v_mfma_f32_16x16x32_bf16 v[38:41], v[194:197], v[154:157], v[38:41]
	v_mfma_f32_16x16x32_bf16 v[34:37], v[202:205], v[154:157], v[34:37]
	v_mfma_f32_16x16x32_bf16 v[22:25], v[194:197], v[162:165], v[22:25]
	v_mfma_f32_16x16x32_bf16 v[18:21], v[202:205], v[162:165], v[18:21]
	v_mfma_f32_16x16x32_bf16 v[6:9], v[194:197], v[170:173], v[6:9]
	v_mfma_f32_16x16x32_bf16 v[2:5], v[202:205], v[170:173], v[2:5]
	v_mfma_f32_16x16x32_bf16 v[54:57], v[198:201], v[150:153], v[54:57]
	v_mfma_f32_16x16x32_bf16 v[50:53], v[206:209], v[150:153], v[50:53]
	v_mfma_f32_16x16x32_bf16 v[38:41], v[198:201], v[158:161], v[38:41]
	v_mfma_f32_16x16x32_bf16 v[34:37], v[206:209], v[158:161], v[34:37]
	v_mfma_f32_16x16x32_bf16 v[22:25], v[198:201], v[166:169], v[22:25]
	v_mfma_f32_16x16x32_bf16 v[18:21], v[206:209], v[166:169], v[18:21]
	v_mfma_f32_16x16x32_bf16 v[6:9], v[198:201], v[174:177], v[6:9]
	v_mfma_f32_16x16x32_bf16 v[2:5], v[206:209], v[174:177], v[2:5]
	s_setprio 0
	s_add_i32 s46, 0, 0x18000
	v_add_u32_e32 v142, s46, v191
	s_barrier
	ds_read_b128 v[130:133], v142
	ds_read_b128 v[134:137], v142 offset:1024
	ds_read_b128 v[138:141], v142 offset:2048
	ds_read_b128 v[142:145], v142 offset:3072
	s_add_u32 s22, s28, 0x80000
	s_addc_u32 s23, s29, 0
	s_mov_b32 m0, s34
	v_lshl_add_u64 v[194:195], s[22:23], 0, v[180:181]
	ds_read_b128 v[146:149], v212 offset:32768
	ds_read_b128 v[150:153], v212 offset:33792
	ds_read_b128 v[154:157], v212 offset:34816
	ds_read_b128 v[158:161], v212 offset:35840
	ds_read_b128 v[162:165], v212 offset:36864
	ds_read_b128 v[166:169], v212 offset:37888
	ds_read_b128 v[170:173], v212 offset:38912
	ds_read_b128 v[174:177], v212 offset:39936
	global_load_lds_dwordx4 v[194:195], off
	v_lshl_add_u64 v[194:195], s[22:23], 0, v[178:179]
	s_mov_b32 m0, s35
	s_nop 0
	global_load_lds_dwordx4 v[194:195], off
	s_waitcnt lgkmcnt(8)
	s_barrier
	s_waitcnt lgkmcnt(0)
	s_setprio 1
	v_mfma_f32_16x16x32_bf16 v[126:129], v[130:133], v[146:149], v[126:129]
	v_mfma_f32_16x16x32_bf16 v[122:125], v[138:141], v[146:149], v[122:125]
	v_mfma_f32_16x16x32_bf16 v[110:113], v[130:133], v[154:157], v[110:113]
	v_mfma_f32_16x16x32_bf16 v[106:109], v[138:141], v[154:157], v[106:109]
	v_mfma_f32_16x16x32_bf16 v[94:97], v[130:133], v[162:165], v[94:97]
	v_mfma_f32_16x16x32_bf16 v[90:93], v[138:141], v[162:165], v[90:93]
	v_mfma_f32_16x16x32_bf16 v[78:81], v[130:133], v[170:173], v[78:81]
	v_mfma_f32_16x16x32_bf16 v[74:77], v[138:141], v[170:173], v[74:77]
	v_mfma_f32_16x16x32_bf16 v[126:129], v[134:137], v[150:153], v[126:129]
	v_mfma_f32_16x16x32_bf16 v[122:125], v[142:145], v[150:153], v[122:125]
	v_mfma_f32_16x16x32_bf16 v[110:113], v[134:137], v[158:161], v[110:113]
	v_mfma_f32_16x16x32_bf16 v[106:109], v[142:145], v[158:161], v[106:109]
	v_mfma_f32_16x16x32_bf16 v[94:97], v[134:137], v[166:169], v[94:97]
	v_mfma_f32_16x16x32_bf16 v[90:93], v[142:145], v[166:169], v[90:93]
	v_mfma_f32_16x16x32_bf16 v[78:81], v[134:137], v[174:177], v[78:81]
	v_mfma_f32_16x16x32_bf16 v[74:77], v[142:145], v[174:177], v[74:77]
	s_setprio 0
	s_barrier
	s_add_i32 s28, 0, 0x1c000
	s_add_i32 s22, s46, s5
	v_add_u32_e32 v206, s28, v191
	v_lshl_add_u64 v[210:211], v[210:211], 0, s[6:7]
	s_mov_b32 m0, s22
	ds_read_b128 v[194:197], v206
	ds_read_b128 v[198:201], v206 offset:1024
	ds_read_b128 v[202:205], v206 offset:2048
	ds_read_b128 v[206:209], v206 offset:3072
	global_load_lds_dwordx4 v[210:211], off
	v_lshl_add_u64 v[210:211], v[220:221], 0, s[6:7]
	s_add_i32 m0, s22, 0x2000
	s_nop 0
	global_load_lds_dwordx4 v[210:211], off
	s_barrier
	s_waitcnt lgkmcnt(0)
	s_setprio 1
	v_mfma_f32_16x16x32_bf16 v[118:121], v[194:197], v[146:149], v[118:121]
	v_mfma_f32_16x16x32_bf16 v[114:117], v[202:205], v[146:149], v[114:117]
	v_mfma_f32_16x16x32_bf16 v[102:105], v[194:197], v[154:157], v[102:105]
	v_mfma_f32_16x16x32_bf16 v[98:101], v[202:205], v[154:157], v[98:101]
	v_mfma_f32_16x16x32_bf16 v[86:89], v[194:197], v[162:165], v[86:89]
	v_mfma_f32_16x16x32_bf16 v[82:85], v[202:205], v[162:165], v[82:85]
	v_mfma_f32_16x16x32_bf16 v[70:73], v[194:197], v[170:173], v[70:73]
	v_mfma_f32_16x16x32_bf16 v[66:69], v[202:205], v[170:173], v[66:69]
	v_mfma_f32_16x16x32_bf16 v[118:121], v[198:201], v[150:153], v[118:121]
	v_mfma_f32_16x16x32_bf16 v[114:117], v[206:209], v[150:153], v[114:117]
	v_mfma_f32_16x16x32_bf16 v[102:105], v[198:201], v[158:161], v[102:105]
	v_mfma_f32_16x16x32_bf16 v[98:101], v[206:209], v[158:161], v[98:101]
	v_mfma_f32_16x16x32_bf16 v[86:89], v[198:201], v[166:169], v[86:89]
	v_mfma_f32_16x16x32_bf16 v[82:85], v[206:209], v[166:169], v[82:85]
	v_mfma_f32_16x16x32_bf16 v[70:73], v[198:201], v[174:177], v[70:73]
	v_mfma_f32_16x16x32_bf16 v[66:69], v[206:209], v[174:177], v[66:69]
	s_setprio 0
	s_mov_b32 m0, s36
	v_lshl_add_u64 v[210:211], v[222:223], 0, s[6:7]
	s_barrier
	ds_read_b128 v[146:149], v212 offset:49152
	ds_read_b128 v[150:153], v212 offset:50176
	ds_read_b128 v[154:157], v212 offset:51200
	ds_read_b128 v[158:161], v212 offset:52224
	ds_read_b128 v[162:165], v212 offset:53248
	ds_read_b128 v[166:169], v212 offset:54272
	ds_read_b128 v[170:173], v212 offset:55296
	ds_read_b128 v[174:177], v212 offset:56320
	global_load_lds_dwordx4 v[210:211], off
	v_lshl_add_u64 v[210:211], v[224:225], 0, s[6:7]
	s_mov_b32 m0, s37
	s_nop 0
	global_load_lds_dwordx4 v[210:211], off
	s_barrier
	s_waitcnt lgkmcnt(0)
	s_setprio 1
	v_mfma_f32_16x16x32_bf16 v[62:65], v[130:133], v[146:149], v[62:65]
	v_mfma_f32_16x16x32_bf16 v[58:61], v[138:141], v[146:149], v[58:61]
	v_mfma_f32_16x16x32_bf16 v[46:49], v[130:133], v[154:157], v[46:49]
	v_mfma_f32_16x16x32_bf16 v[42:45], v[138:141], v[154:157], v[42:45]
	v_mfma_f32_16x16x32_bf16 v[30:33], v[130:133], v[162:165], v[30:33]
	v_mfma_f32_16x16x32_bf16 v[26:29], v[138:141], v[162:165], v[26:29]
	v_mfma_f32_16x16x32_bf16 v[14:17], v[130:133], v[170:173], v[14:17]
	v_mfma_f32_16x16x32_bf16 v[10:13], v[138:141], v[170:173], v[10:13]
	v_mfma_f32_16x16x32_bf16 v[62:65], v[134:137], v[150:153], v[62:65]
	v_mfma_f32_16x16x32_bf16 v[58:61], v[142:145], v[150:153], v[58:61]
	v_mfma_f32_16x16x32_bf16 v[46:49], v[134:137], v[158:161], v[46:49]
	v_mfma_f32_16x16x32_bf16 v[42:45], v[142:145], v[158:161], v[42:45]
	v_mfma_f32_16x16x32_bf16 v[30:33], v[134:137], v[166:169], v[30:33]
	v_mfma_f32_16x16x32_bf16 v[26:29], v[142:145], v[166:169], v[26:29]
	v_mfma_f32_16x16x32_bf16 v[14:17], v[134:137], v[174:177], v[14:17]
	v_mfma_f32_16x16x32_bf16 v[10:13], v[142:145], v[174:177], v[10:13]
	s_setprio 0
	s_barrier
	s_add_u32 s22, s26, 0x80080
	s_addc_u32 s23, s27, 0
	s_add_i32 s26, s28, s5
	v_lshl_add_u64 v[130:131], s[22:23], 0, v[180:181]
	s_mov_b32 m0, s26
	s_nop 0
	global_load_lds_dwordx4 v[130:131], off
	v_lshl_add_u64 v[130:131], s[22:23], 0, v[178:179]
	s_add_i32 m0, s26, 0x2000
	s_nop 0
	global_load_lds_dwordx4 v[130:131], off
	s_waitcnt vmcnt(6)
	s_barrier
	s_setprio 1
	v_mfma_f32_16x16x32_bf16 v[54:57], v[194:197], v[146:149], v[54:57]
	v_mfma_f32_16x16x32_bf16 v[50:53], v[202:205], v[146:149], v[50:53]
	v_mfma_f32_16x16x32_bf16 v[38:41], v[194:197], v[154:157], v[38:41]
	v_mfma_f32_16x16x32_bf16 v[34:37], v[202:205], v[154:157], v[34:37]
	v_mfma_f32_16x16x32_bf16 v[22:25], v[194:197], v[162:165], v[22:25]
	v_mfma_f32_16x16x32_bf16 v[18:21], v[202:205], v[162:165], v[18:21]
	v_mfma_f32_16x16x32_bf16 v[6:9], v[194:197], v[170:173], v[6:9]
	v_mfma_f32_16x16x32_bf16 v[2:5], v[202:205], v[170:173], v[2:5]
	v_mfma_f32_16x16x32_bf16 v[54:57], v[198:201], v[150:153], v[54:57]
	v_mfma_f32_16x16x32_bf16 v[50:53], v[206:209], v[150:153], v[50:53]
	v_mfma_f32_16x16x32_bf16 v[38:41], v[198:201], v[158:161], v[38:41]
	v_mfma_f32_16x16x32_bf16 v[34:37], v[206:209], v[158:161], v[34:37]
	v_mfma_f32_16x16x32_bf16 v[22:25], v[198:201], v[166:169], v[22:25]
	v_mfma_f32_16x16x32_bf16 v[18:21], v[206:209], v[166:169], v[18:21]
	v_mfma_f32_16x16x32_bf16 v[6:9], v[198:201], v[174:177], v[6:9]
	v_mfma_f32_16x16x32_bf16 v[2:5], v[206:209], v[174:177], v[2:5]
	s_setprio 0
	s_add_i32 s45, s45, 2
	s_add_u32 s43, s43, 0x100
	s_addc_u32 s44, s44, 0
	s_cmp_gt_u32 s45, 29
	s_mov_b64 s[22:23], s[24:25]
	s_barrier
	s_cbranch_scc0 .LBB0_47
	s_nop 0
	s_nop 0
	s_nop 0
	s_nop 0
	s_nop 0
	s_nop 0
	v_lshl_add_u32 v196, s39, 8, v1
	v_lshl_or_b32 v194, s40, 8, v192
	v_readlane_b32 s24, v254, 46
	v_ashrrev_i32_e32 v195, 31, v194
	v_ashrrev_i32_e32 v197, 31, v196
	v_readlane_b32 s25, v254, 47
	v_or_b32_e32 v210, 16, v196
	v_lshlrev_b64 v[130:131], 13, v[196:197]
	v_lshl_add_u64 v[198:199], v[194:195], 2, s[24:25]
	v_or_b32_e32 v206, 32, v196
	v_or_b32_e32 v202, 48, v196
	v_ashrrev_i32_e32 v211, 31, v210
	v_lshl_add_u64 v[224:225], v[198:199], 0, v[130:131]
	v_ashrrev_i32_e32 v207, 31, v206
	v_ashrrev_i32_e32 v203, 31, v202
	v_lshlrev_b64 v[130:131], 13, v[210:211]
	global_load_dwordx4 v[220:223], v[224:225], off
	global_load_dwordx4 v[236:239], v[224:225], off offset:64
	global_load_dwordx4 v[240:243], v[224:225], off offset:512
	global_load_dwordx4 v[244:247], v[224:225], off offset:576
	v_lshlrev_b64 v[132:133], 13, v[206:207]
	v_lshlrev_b64 v[134:135], 13, v[202:203]
	v_lshl_add_u64 v[208:209], v[198:199], 0, v[130:131]
	v_lshl_add_u64 v[204:205], v[198:199], 0, v[132:133]
	v_lshl_add_u64 v[200:201], v[198:199], 0, v[134:135]
	global_load_dwordx4 v[174:177], v[208:209], off
	global_load_dwordx4 v[170:173], v[208:209], off offset:64
	global_load_dwordx4 v[166:169], v[208:209], off offset:512
	global_load_dwordx4 v[162:165], v[208:209], off offset:576
	global_load_dwordx4 v[158:161], v[204:205], off
	global_load_dwordx4 v[154:157], v[204:205], off offset:64
	global_load_dwordx4 v[150:153], v[204:205], off offset:512
	global_load_dwordx4 v[146:149], v[204:205], off offset:576
	global_load_dwordx4 v[142:145], v[200:201], off
	global_load_dwordx4 v[138:141], v[200:201], off offset:64
	global_load_dwordx4 v[134:137], v[200:201], off offset:512
	global_load_dwordx4 v[130:133], v[200:201], off offset:576
	v_lshlrev_b64 v[248:249], 11, v[196:197]
	v_readlane_b32 s22, v252, 5
	v_lshl_add_u64 v[248:249], v[248:249], 0, v[194:195]
	v_readlane_b32 s23, v252, 6
	v_readlane_b32 s26, v254, 48
	v_readlane_b32 s27, v254, 49
	v_lshl_add_u64 v[248:249], v[248:249], 1, s[22:23]
	v_readlane_b32 s22, v252, 9
	v_readlane_b32 s23, v252, 10
	s_waitcnt vmcnt(0)
	v_pk_add_f32 v[128:129], v[128:129], v[222:223]
	v_pk_add_f32 v[126:127], v[126:127], v[220:221]
	v_pk_add_f32 v[122:123], v[122:123], v[236:237]
	v_pk_add_f32 v[118:119], v[118:119], v[240:241]
	global_store_dwordx4 v[224:225], v[126:129], off
	v_cvt_pk_bf16_f32 v220, v126, v127
	v_mul_f32_e32 v213, v123, v123
	v_mul_f32_e32 v127, v127, v127
	v_pk_add_f32 v[124:125], v[124:125], v[238:239]
	v_pk_add_f32 v[114:115], v[114:115], v[244:245]
	v_mul_f32_e32 v226, v119, v119
	v_fmac_f32_e32 v127, v126, v126
	v_fmac_f32_e32 v213, v122, v122
	v_pk_add_f32 v[120:121], v[120:121], v[242:243]
	v_mul_f32_e32 v235, v115, v115
	v_fmac_f32_e32 v226, v118, v118
	v_fmac_f32_e32 v127, v128, v128
	v_fmac_f32_e32 v213, v124, v124
	v_pk_add_f32 v[116:117], v[116:117], v[246:247]
	v_cvt_pk_bf16_f32 v221, v128, v129
	v_fmac_f32_e32 v235, v114, v114
	v_fmac_f32_e32 v226, v120, v120
	v_fmac_f32_e32 v127, v129, v129
	v_fmac_f32_e32 v213, v125, v125
	v_cvt_pk_bf16_f32 v222, v122, v123
	v_cvt_pk_bf16_f32 v223, v124, v125
	v_cvt_pk_bf16_f32 v236, v118, v119
	v_cvt_pk_bf16_f32 v237, v120, v121
	v_cvt_pk_bf16_f32 v238, v114, v115
	v_cvt_pk_bf16_f32 v239, v116, v117
	global_store_dwordx2 v[248:249], v[220:221], off
	global_store_dwordx4 v[224:225], v[122:125], off offset:64
	global_store_dwordx2 v[248:249], v[222:223], off offset:32
	global_store_dwordx4 v[224:225], v[118:121], off offset:512
	global_store_dwordx2 v[248:249], v[236:237], off offset:256
	global_store_dwordx4 v[224:225], v[114:117], off offset:576
	global_store_dwordx2 v[248:249], v[238:239], off offset:288
	v_fmac_f32_e32 v235, v116, v116
	v_fmac_f32_e32 v226, v121, v121
	v_add_f32_e32 v114, v127, v213
	v_fmac_f32_e32 v235, v117, v117
	v_add_f32_e32 v114, v114, v226
	v_add_f32_e32 v114, v114, v235
	v_mov_b32_e32 v115, v114
	s_nop 1
	v_permlane32_swap_b32_e32 v114, v115
	v_add_f32_e32 v116, v114, v115
	v_mov_b32_e32 v117, v116
	s_nop 1
	v_permlane16_swap_b32_e32 v116, v117
	v_lshl_add_u64 v[114:115], v[196:197], 2, s[22:23]
	s_and_saveexec_b64 s[22:23], s[10:11]
	s_cbranch_execz .LBB0_50
	v_add_f32_e32 v116, v116, v117
	global_atomic_add_f32 v[114:115], v116, off

.LBB0_163:
	s_add_u32 s14, s12, 0xfff80080
	s_addc_u32 s15, s13, -1
	s_add_i32 s47, 0, 0x10000
	v_add_u32_e32 v94, s47, v184
	ds_read_b128 v[82:85], v94
	ds_read_b128 v[86:89], v94 offset:1024
	ds_read_b128 v[90:93], v94 offset:2048
	ds_read_b128 v[94:97], v94 offset:3072
	s_cmp_eq_u32 s46, 28
	s_cselect_b32 s17, s25, s15
	s_cselect_b32 s16, s31, s14
	s_cselect_b32 s15, s23, s45
	s_cselect_b32 s14, s35, s44
	v_lshl_add_u64 v[212:213], s[12:13], 0, v[176:177]
	s_add_i32 m0, s37, 0xc000
	ds_read_b128 v[106:109], v207
	ds_read_b128 v[110:113], v207 offset:1024
	ds_read_b128 v[122:125], v207 offset:2048
	ds_read_b128 v[126:129], v207 offset:3072
	ds_read_b128 v[162:165], v207 offset:4096
	ds_read_b128 v[166:169], v207 offset:5120
	ds_read_b128 v[180:183], v207 offset:6144
	ds_read_b128 v[208:211], v207 offset:7168
	global_load_lds_dwordx4 v[212:213], off
	v_lshl_add_u64 v[212:213], s[12:13], 0, v[178:179]
	s_add_i32 m0, s37, 0xe000
	s_nop 0
	global_load_lds_dwordx4 v[212:213], off
	s_waitcnt lgkmcnt(8)
	s_barrier
	s_waitcnt lgkmcnt(0)
	s_setprio 1
	v_mfma_f32_16x16x32_bf16 v[158:161], v[82:85], v[106:109], v[158:161]
	v_mfma_f32_16x16x32_bf16 v[154:157], v[90:93], v[106:109], v[154:157]
	v_mfma_f32_16x16x32_bf16 v[150:153], v[82:85], v[122:125], v[150:153]
	v_mfma_f32_16x16x32_bf16 v[146:149], v[90:93], v[122:125], v[146:149]
	v_mfma_f32_16x16x32_bf16 v[142:145], v[82:85], v[162:165], v[142:145]
	v_mfma_f32_16x16x32_bf16 v[138:141], v[90:93], v[162:165], v[138:141]
	v_mfma_f32_16x16x32_bf16 v[134:137], v[82:85], v[180:183], v[134:137]
	v_mfma_f32_16x16x32_bf16 v[130:133], v[90:93], v[180:183], v[130:133]
	v_mfma_f32_16x16x32_bf16 v[158:161], v[86:89], v[110:113], v[158:161]
	v_mfma_f32_16x16x32_bf16 v[154:157], v[94:97], v[110:113], v[154:157]
	v_mfma_f32_16x16x32_bf16 v[150:153], v[86:89], v[126:129], v[150:153]
	v_mfma_f32_16x16x32_bf16 v[146:149], v[94:97], v[126:129], v[146:149]
	v_mfma_f32_16x16x32_bf16 v[142:145], v[86:89], v[166:169], v[142:145]
	v_mfma_f32_16x16x32_bf16 v[138:141], v[94:97], v[166:169], v[138:141]
	v_mfma_f32_16x16x32_bf16 v[134:137], v[86:89], v[208:211], v[134:137]
	v_mfma_f32_16x16x32_bf16 v[130:133], v[94:97], v[208:211], v[130:133]
	s_setprio 0
	s_barrier
	s_add_i32 s50, 0, 0x14000
	v_add_u32_e32 v212, s50, v184
	s_add_i32 s47, s47, s36
	ds_read_b128 v[220:223], v212
	ds_read_b128 v[236:239], v212 offset:1024
	ds_read_b128 v[240:243], v212 offset:2048
	ds_read_b128 v[244:247], v212 offset:3072
	v_lshl_add_u64 v[212:213], s[14:15], 0, v[172:173]
	s_mov_b32 m0, s47
	v_lshl_add_u64 v[224:225], s[14:15], 0, v[170:171]
	global_load_lds_dwordx4 v[212:213], off
	s_add_i32 m0, s47, 0x2000
	s_nop 0
	global_load_lds_dwordx4 v[224:225], off
	s_barrier
	s_waitcnt lgkmcnt(0)
	s_setprio 1
	v_mfma_f32_16x16x32_bf16 v[118:121], v[220:223], v[106:109], v[118:121]
	v_mfma_f32_16x16x32_bf16 v[102:105], v[220:223], v[122:125], v[102:105]
	v_mfma_f32_16x16x32_bf16 v[98:101], v[240:243], v[122:125], v[98:101]
	v_mfma_f32_16x16x32_bf16 v[78:81], v[220:223], v[162:165], v[78:81]
	v_mfma_f32_16x16x32_bf16 v[74:77], v[240:243], v[162:165], v[74:77]
	v_mfma_f32_16x16x32_bf16 v[70:73], v[220:223], v[180:183], v[70:73]
	v_mfma_f32_16x16x32_bf16 v[66:69], v[240:243], v[180:183], v[66:69]
	v_mfma_f32_16x16x32_bf16 v[118:121], v[236:239], v[110:113], v[118:121]
	v_mfma_f32_16x16x32_bf16 v[106:109], v[240:243], v[106:109], v[114:117]
	v_mfma_f32_16x16x32_bf16 v[102:105], v[236:239], v[126:129], v[102:105]
	v_mfma_f32_16x16x32_bf16 v[98:101], v[244:247], v[126:129], v[98:101]
	v_mfma_f32_16x16x32_bf16 v[78:81], v[236:239], v[166:169], v[78:81]
	v_mfma_f32_16x16x32_bf16 v[74:77], v[244:247], v[166:169], v[74:77]
	v_mfma_f32_16x16x32_bf16 v[70:73], v[236:239], v[208:211], v[70:73]
	v_mfma_f32_16x16x32_bf16 v[66:69], v[244:247], v[208:211], v[66:69]
	v_mfma_f32_16x16x32_bf16 v[106:109], v[244:247], v[110:113], v[106:109]
	s_setprio 0
	s_mov_b32 m0, s37
	v_lshl_add_u64 v[248:249], s[16:17], 0, v[172:173]
	s_barrier
	ds_read_b128 v[110:113], v207 offset:16384
	ds_read_b128 v[114:117], v207 offset:17408
	ds_read_b128 v[122:125], v207 offset:18432
	ds_read_b128 v[126:129], v207 offset:19456
	ds_read_b128 v[162:165], v207 offset:20480
	ds_read_b128 v[166:169], v207 offset:21504
	ds_read_b128 v[180:183], v207 offset:22528
	ds_read_b128 v[208:211], v207 offset:23552
	global_load_lds_dwordx4 v[248:249], off
	v_lshl_add_u64 v[250:251], s[16:17], 0, v[170:171]
	s_mov_b32 m0, s38
	s_nop 0
	global_load_lds_dwordx4 v[250:251], off
	s_barrier
	s_waitcnt lgkmcnt(0)
	s_setprio 1
	v_mfma_f32_16x16x32_bf16 v[62:65], v[82:85], v[110:113], v[62:65]
	v_mfma_f32_16x16x32_bf16 v[58:61], v[90:93], v[110:113], v[58:61]
	v_mfma_f32_16x16x32_bf16 v[54:57], v[82:85], v[122:125], v[54:57]
	v_mfma_f32_16x16x32_bf16 v[50:53], v[90:93], v[122:125], v[50:53]
	v_mfma_f32_16x16x32_bf16 v[46:49], v[82:85], v[162:165], v[46:49]
	v_mfma_f32_16x16x32_bf16 v[42:45], v[90:93], v[162:165], v[42:45]
	v_mfma_f32_16x16x32_bf16 v[38:41], v[82:85], v[180:183], v[38:41]
	v_mfma_f32_16x16x32_bf16 v[34:37], v[90:93], v[180:183], v[34:37]
	v_mfma_f32_16x16x32_bf16 v[62:65], v[86:89], v[114:117], v[62:65]
	v_mfma_f32_16x16x32_bf16 v[58:61], v[94:97], v[114:117], v[58:61]
	v_mfma_f32_16x16x32_bf16 v[54:57], v[86:89], v[126:129], v[54:57]
	v_mfma_f32_16x16x32_bf16 v[50:53], v[94:97], v[126:129], v[50:53]
	v_mfma_f32_16x16x32_bf16 v[46:49], v[86:89], v[166:169], v[46:49]
	v_mfma_f32_16x16x32_bf16 v[42:45], v[94:97], v[166:169], v[42:45]
	v_mfma_f32_16x16x32_bf16 v[38:41], v[86:89], v[208:211], v[38:41]
	v_mfma_f32_16x16x32_bf16 v[34:37], v[94:97], v[208:211], v[34:37]
	s_setprio 0
	s_barrier
	s_add_u32 s48, s14, 0x80000
	s_addc_u32 s49, s15, 0
	s_add_i32 s47, s50, s36
	v_lshl_add_u64 v[82:83], s[48:49], 0, v[172:173]
	s_mov_b32 m0, s47
	s_nop 0
	global_load_lds_dwordx4 v[82:83], off
	v_lshl_add_u64 v[82:83], s[48:49], 0, v[170:171]
	s_add_i32 m0, s47, 0x2000
	s_nop 0
	global_load_lds_dwordx4 v[82:83], off
	s_waitcnt vmcnt(6)
	s_barrier
	s_setprio 1
	v_mfma_f32_16x16x32_bf16 v[30:33], v[220:223], v[110:113], v[30:33]
	v_mfma_f32_16x16x32_bf16 v[26:29], v[240:243], v[110:113], v[26:29]
	v_mfma_f32_16x16x32_bf16 v[22:25], v[220:223], v[122:125], v[22:25]
	v_mfma_f32_16x16x32_bf16 v[18:21], v[240:243], v[122:125], v[18:21]
	v_mfma_f32_16x16x32_bf16 v[14:17], v[220:223], v[162:165], v[14:17]
	v_mfma_f32_16x16x32_bf16 v[10:13], v[240:243], v[162:165], v[10:13]
	v_mfma_f32_16x16x32_bf16 v[6:9], v[220:223], v[180:183], v[6:9]
	v_mfma_f32_16x16x32_bf16 v[2:5], v[240:243], v[180:183], v[2:5]
	v_mfma_f32_16x16x32_bf16 v[30:33], v[236:239], v[114:117], v[30:33]
	v_mfma_f32_16x16x32_bf16 v[26:29], v[244:247], v[114:117], v[26:29]
	v_mfma_f32_16x16x32_bf16 v[22:25], v[236:239], v[126:129], v[22:25]
	v_mfma_f32_16x16x32_bf16 v[18:21], v[244:247], v[126:129], v[18:21]
	v_mfma_f32_16x16x32_bf16 v[14:17], v[236:239], v[166:169], v[14:17]
	v_mfma_f32_16x16x32_bf16 v[10:13], v[244:247], v[166:169], v[10:13]
	v_mfma_f32_16x16x32_bf16 v[6:9], v[236:239], v[208:211], v[6:9]
	v_mfma_f32_16x16x32_bf16 v[2:5], v[244:247], v[208:211], v[2:5]
	s_setprio 0
	s_add_i32 s47, 0, 0x18000
	v_add_u32_e32 v94, s47, v184
	s_barrier
	ds_read_b128 v[82:85], v94
	ds_read_b128 v[86:89], v94 offset:1024
	ds_read_b128 v[90:93], v94 offset:2048
	ds_read_b128 v[94:97], v94 offset:3072
	s_add_u32 s16, s16, 0x80000
	s_addc_u32 s17, s17, 0
	s_mov_b32 m0, s39
	v_lshl_add_u64 v[220:221], s[16:17], 0, v[172:173]
	ds_read_b128 v[110:113], v207 offset:32768
	ds_read_b128 v[114:117], v207 offset:33792
	ds_read_b128 v[122:125], v207 offset:34816
	ds_read_b128 v[126:129], v207 offset:35840
	ds_read_b128 v[162:165], v207 offset:36864
	ds_read_b128 v[166:169], v207 offset:37888
	ds_read_b128 v[180:183], v207 offset:38912
	ds_read_b128 v[208:211], v207 offset:39936
	global_load_lds_dwordx4 v[220:221], off
	v_lshl_add_u64 v[220:221], s[16:17], 0, v[170:171]
	s_mov_b32 m0, s40
	s_nop 0
	global_load_lds_dwordx4 v[220:221], off
	s_waitcnt lgkmcnt(8)
	s_barrier
	s_waitcnt lgkmcnt(0)
	s_setprio 1
	v_mfma_f32_16x16x32_bf16 v[158:161], v[82:85], v[110:113], v[158:161]
	v_mfma_f32_16x16x32_bf16 v[154:157], v[90:93], v[110:113], v[154:157]
	v_mfma_f32_16x16x32_bf16 v[150:153], v[82:85], v[122:125], v[150:153]
	v_mfma_f32_16x16x32_bf16 v[146:149], v[90:93], v[122:125], v[146:149]
	v_mfma_f32_16x16x32_bf16 v[142:145], v[82:85], v[162:165], v[142:145]
	v_mfma_f32_16x16x32_bf16 v[138:141], v[90:93], v[162:165], v[138:141]
	v_mfma_f32_16x16x32_bf16 v[134:137], v[82:85], v[180:183], v[134:137]
	v_mfma_f32_16x16x32_bf16 v[130:133], v[90:93], v[180:183], v[130:133]
	v_mfma_f32_16x16x32_bf16 v[158:161], v[86:89], v[114:117], v[158:161]
	v_mfma_f32_16x16x32_bf16 v[154:157], v[94:97], v[114:117], v[154:157]
	v_mfma_f32_16x16x32_bf16 v[150:153], v[86:89], v[126:129], v[150:153]
	v_mfma_f32_16x16x32_bf16 v[146:149], v[94:97], v[126:129], v[146:149]
	v_mfma_f32_16x16x32_bf16 v[142:145], v[86:89], v[166:169], v[142:145]
	v_mfma_f32_16x16x32_bf16 v[138:141], v[94:97], v[166:169], v[138:141]
	v_mfma_f32_16x16x32_bf16 v[134:137], v[86:89], v[208:211], v[134:137]
	v_mfma_f32_16x16x32_bf16 v[130:133], v[94:97], v[208:211], v[130:133]
	s_setprio 0
	s_barrier
	s_add_i32 s16, 0, 0x1c000
	s_add_i32 s17, s47, s36
	v_add_u32_e32 v226, s16, v184
	v_lshl_add_u64 v[212:213], v[212:213], 0, s[6:7]
	s_mov_b32 m0, s17
	ds_read_b128 v[220:223], v226
	ds_read_b128 v[236:239], v226 offset:1024
	ds_read_b128 v[240:243], v226 offset:2048
	ds_read_b128 v[244:247], v226 offset:3072
	global_load_lds_dwordx4 v[212:213], off
	v_lshl_add_u64 v[212:213], v[224:225], 0, s[6:7]
	s_add_i32 m0, s17, 0x2000
	s_nop 0
	global_load_lds_dwordx4 v[212:213], off
	s_barrier
	s_waitcnt lgkmcnt(0)
	s_setprio 1
	v_mfma_f32_16x16x32_bf16 v[118:121], v[220:223], v[110:113], v[118:121]
	v_mfma_f32_16x16x32_bf16 v[106:109], v[240:243], v[110:113], v[106:109]
	v_mfma_f32_16x16x32_bf16 v[102:105], v[220:223], v[122:125], v[102:105]
	v_mfma_f32_16x16x32_bf16 v[98:101], v[240:243], v[122:125], v[98:101]
	v_mfma_f32_16x16x32_bf16 v[78:81], v[220:223], v[162:165], v[78:81]
	v_mfma_f32_16x16x32_bf16 v[74:77], v[240:243], v[162:165], v[74:77]
	v_mfma_f32_16x16x32_bf16 v[70:73], v[220:223], v[180:183], v[70:73]
	v_mfma_f32_16x16x32_bf16 v[66:69], v[240:243], v[180:183], v[66:69]
	v_mfma_f32_16x16x32_bf16 v[118:121], v[236:239], v[114:117], v[118:121]
	v_mfma_f32_16x16x32_bf16 v[114:117], v[244:247], v[114:117], v[106:109]
	v_mfma_f32_16x16x32_bf16 v[102:105], v[236:239], v[126:129], v[102:105]
	v_mfma_f32_16x16x32_bf16 v[98:101], v[244:247], v[126:129], v[98:101]
	v_mfma_f32_16x16x32_bf16 v[78:81], v[236:239], v[166:169], v[78:81]
	v_mfma_f32_16x16x32_bf16 v[74:77], v[244:247], v[166:169], v[74:77]
	v_mfma_f32_16x16x32_bf16 v[70:73], v[236:239], v[208:211], v[70:73]
	v_mfma_f32_16x16x32_bf16 v[66:69], v[244:247], v[208:211], v[66:69]
	s_setprio 0
	s_mov_b32 m0, s41
	v_lshl_add_u64 v[212:213], v[248:249], 0, s[6:7]
	s_barrier
	ds_read_b128 v[106:109], v207 offset:49152
	ds_read_b128 v[110:113], v207 offset:50176
	ds_read_b128 v[122:125], v207 offset:51200
	ds_read_b128 v[126:129], v207 offset:52224
	ds_read_b128 v[162:165], v207 offset:53248
	ds_read_b128 v[166:169], v207 offset:54272
	ds_read_b128 v[180:183], v207 offset:55296
	ds_read_b128 v[208:211], v207 offset:56320
	global_load_lds_dwordx4 v[212:213], off
	v_lshl_add_u64 v[212:213], v[250:251], 0, s[6:7]
	s_mov_b32 m0, s42
	s_nop 0
	global_load_lds_dwordx4 v[212:213], off
	s_barrier
	s_waitcnt lgkmcnt(0)
	s_setprio 1
	v_mfma_f32_16x16x32_bf16 v[62:65], v[82:85], v[106:109], v[62:65]
	v_mfma_f32_16x16x32_bf16 v[58:61], v[90:93], v[106:109], v[58:61]
	v_mfma_f32_16x16x32_bf16 v[54:57], v[82:85], v[122:125], v[54:57]
	v_mfma_f32_16x16x32_bf16 v[50:53], v[90:93], v[122:125], v[50:53]
	v_mfma_f32_16x16x32_bf16 v[46:49], v[82:85], v[162:165], v[46:49]
	v_mfma_f32_16x16x32_bf16 v[42:45], v[90:93], v[162:165], v[42:45]
	v_mfma_f32_16x16x32_bf16 v[38:41], v[82:85], v[180:183], v[38:41]
	v_mfma_f32_16x16x32_bf16 v[34:37], v[90:93], v[180:183], v[34:37]
	v_mfma_f32_16x16x32_bf16 v[62:65], v[86:89], v[110:113], v[62:65]
	v_mfma_f32_16x16x32_bf16 v[58:61], v[94:97], v[110:113], v[58:61]
	v_mfma_f32_16x16x32_bf16 v[54:57], v[86:89], v[126:129], v[54:57]
	v_mfma_f32_16x16x32_bf16 v[50:53], v[94:97], v[126:129], v[50:53]
	v_mfma_f32_16x16x32_bf16 v[46:49], v[86:89], v[166:169], v[46:49]
	v_mfma_f32_16x16x32_bf16 v[42:45], v[94:97], v[166:169], v[42:45]
	v_mfma_f32_16x16x32_bf16 v[38:41], v[86:89], v[208:211], v[38:41]
	v_mfma_f32_16x16x32_bf16 v[34:37], v[94:97], v[208:211], v[34:37]
	s_setprio 0
	s_barrier
	s_add_u32 s14, s14, 0x80080
	s_addc_u32 s15, s15, 0
	s_add_i32 s16, s16, s36
	v_lshl_add_u64 v[82:83], s[14:15], 0, v[172:173]
	s_mov_b32 m0, s16
	s_nop 0
	global_load_lds_dwordx4 v[82:83], off
	v_lshl_add_u64 v[82:83], s[14:15], 0, v[170:171]
	s_add_i32 m0, s16, 0x2000
	s_nop 0
	global_load_lds_dwordx4 v[82:83], off
	s_waitcnt vmcnt(6)
	s_barrier
	s_setprio 1
	v_mfma_f32_16x16x32_bf16 v[30:33], v[220:223], v[106:109], v[30:33]
	v_mfma_f32_16x16x32_bf16 v[26:29], v[240:243], v[106:109], v[26:29]
	v_mfma_f32_16x16x32_bf16 v[22:25], v[220:223], v[122:125], v[22:25]
	v_mfma_f32_16x16x32_bf16 v[18:21], v[240:243], v[122:125], v[18:21]
	v_mfma_f32_16x16x32_bf16 v[14:17], v[220:223], v[162:165], v[14:17]
	v_mfma_f32_16x16x32_bf16 v[10:13], v[240:243], v[162:165], v[10:13]
	v_mfma_f32_16x16x32_bf16 v[6:9], v[220:223], v[180:183], v[6:9]
	v_mfma_f32_16x16x32_bf16 v[2:5], v[240:243], v[180:183], v[2:5]
	v_mfma_f32_16x16x32_bf16 v[30:33], v[236:239], v[110:113], v[30:33]
	v_mfma_f32_16x16x32_bf16 v[26:29], v[244:247], v[110:113], v[26:29]
	v_mfma_f32_16x16x32_bf16 v[22:25], v[236:239], v[126:129], v[22:25]
	v_mfma_f32_16x16x32_bf16 v[18:21], v[244:247], v[126:129], v[18:21]
	v_mfma_f32_16x16x32_bf16 v[14:17], v[236:239], v[166:169], v[14:17]
	v_mfma_f32_16x16x32_bf16 v[10:13], v[244:247], v[166:169], v[10:13]
	v_mfma_f32_16x16x32_bf16 v[6:9], v[236:239], v[208:211], v[6:9]
	v_mfma_f32_16x16x32_bf16 v[2:5], v[244:247], v[208:211], v[2:5]
	s_setprio 0
	s_add_i32 s46, s46, 2
	s_add_u32 s12, s12, 0x100
	s_addc_u32 s13, s13, 0
	s_add_u32 s44, s44, 0x100
	s_addc_u32 s45, s45, 0
	s_cmp_gt_u32 s46, 29
	s_barrier
	s_cbranch_scc0 .LBB0_163
	s_nop 0
	s_nop 0
	s_nop 0
	s_nop 0
	s_nop 0
	s_nop 0
	s_lshl_b32 s23, s30, 8
	v_add_u32_e32 v180, s23, v1
	v_mov_b32_e32 v162, 0
	v_cndmask_b32_e64 v182, 0, 1, s[20:21]
	v_lshlrev_b32_e32 v209, 5, v180
	v_cmp_ne_u32_e64 s[16:17], 1, v182
	s_andn2_b64 vcc, exec, s[20:21]
	v_mov_b32_e32 v163, v162
	v_mov_b32_e32 v164, v162
	v_mov_b32_e32 v165, v162
	v_mov_b32_e32 v122, v162
	v_mov_b32_e32 v123, v162
	v_mov_b32_e32 v124, v162
	v_mov_b32_e32 v125, v162
	v_mov_b32_e32 v106, v162
	v_mov_b32_e32 v107, v162
	v_mov_b32_e32 v108, v162
	v_mov_b32_e32 v109, v162
	v_mov_b32_e32 v86, v162
	v_mov_b32_e32 v87, v162
	v_mov_b32_e32 v88, v162
	v_mov_b32_e32 v89, v162
	v_mov_b32_e32 v82, v162
	v_mov_b32_e32 v83, v162
	v_mov_b32_e32 v84, v162
	v_mov_b32_e32 v85, v162
	v_mov_b32_e32 v166, v162
	v_mov_b32_e32 v167, v162
	v_mov_b32_e32 v168, v162
	v_mov_b32_e32 v169, v162
	v_mov_b32_e32 v126, v162
	v_mov_b32_e32 v127, v162
	v_mov_b32_e32 v128, v162
	v_mov_b32_e32 v129, v162
	v_mov_b32_e32 v110, v162
	v_mov_b32_e32 v111, v162
	v_mov_b32_e32 v112, v162
	v_mov_b32_e32 v113, v162
	v_mov_b32_e32 v90, v162
	v_mov_b32_e32 v91, v162
	v_mov_b32_e32 v92, v162
	v_mov_b32_e32 v93, v162
	v_mov_b32_e32 v94, v162
	v_mov_b32_e32 v95, v162
	v_mov_b32_e32 v96, v162
	v_mov_b32_e32 v97, v162
	s_cbranch_vccnz .LBB0_166
	v_and_b32_e32 v82, 0x1f9e0, v209
	v_lshlrev_b32_e32 v82, 2, v82
	v_mov_b32_e32 v83, v0
	v_lshl_add_u64 v[82:83], v[174:175], 0, v[82:83]
	v_add_co_u32_e32 v84, vcc, 0x1000, v82
	s_nop 1
	v_addc_co_u32_e32 v85, vcc, 0, v83, vcc
	global_load_dwordx4 v[162:165], v[84:85], off offset:2112
	global_load_dwordx4 v[166:169], v[84:85], off offset:2048
	global_load_dwordx4 v[126:129], v[82:83], off
	global_load_dwordx4 v[122:125], v[82:83], off offset:64
	global_load_dwordx4 v[110:113], v[82:83], off offset:2048
	global_load_dwordx4 v[106:109], v[82:83], off offset:2112
	global_load_dwordx4 v[90:93], v[84:85], off
	global_load_dwordx4 v[86:89], v[84:85], off offset:64
	s_waitcnt vmcnt(0)
	v_mov_b32_e32 v82, v162
	v_mov_b32_e32 v83, v163
	v_mov_b32_e32 v84, v164
	v_mov_b32_e32 v85, v165
	v_mov_b32_e32 v94, v166
	v_mov_b32_e32 v95, v167
	v_mov_b32_e32 v96, v168
	v_mov_b32_e32 v97, v169

.LBB0_253:
	s_add_u32 s24, s22, 0x100
	s_addc_u32 s25, s23, 0
	s_add_i32 s46, 0, 0x10000
	v_add_u32_e32 v142, s46, v191
	ds_read_b128 v[130:133], v142
	ds_read_b128 v[134:137], v142 offset:1024
	ds_read_b128 v[138:141], v142 offset:2048
	ds_read_b128 v[142:145], v142 offset:3072
	s_cmp_eq_u32 s45, 28
	s_cselect_b32 s29, s17, s25
	s_cselect_b32 s28, s41, s24
	s_cselect_b32 s27, s15, s44
	s_cselect_b32 s26, s42, s43
	v_lshl_add_u64 v[194:195], s[22:23], 0, v[182:183]
	s_add_i32 m0, s30, 0xc000
	ds_read_b128 v[146:149], v212
	ds_read_b128 v[150:153], v212 offset:1024
	ds_read_b128 v[154:157], v212 offset:2048
	ds_read_b128 v[158:161], v212 offset:3072
	ds_read_b128 v[162:165], v212 offset:4096
	ds_read_b128 v[166:169], v212 offset:5120
	ds_read_b128 v[170:173], v212 offset:6144
	ds_read_b128 v[174:177], v212 offset:7168
	global_load_lds_dwordx4 v[194:195], off
	v_lshl_add_u64 v[194:195], s[22:23], 0, v[184:185]
	s_add_i32 m0, s30, 0xe000
	s_nop 0
	global_load_lds_dwordx4 v[194:195], off
	s_waitcnt lgkmcnt(8)
	s_barrier
	s_waitcnt lgkmcnt(0)
	s_setprio 1
	v_mfma_f32_16x16x32_bf16 v[126:129], v[130:133], v[146:149], v[126:129]
	v_mfma_f32_16x16x32_bf16 v[122:125], v[138:141], v[146:149], v[122:125]
	v_mfma_f32_16x16x32_bf16 v[110:113], v[130:133], v[154:157], v[110:113]
	v_mfma_f32_16x16x32_bf16 v[106:109], v[138:141], v[154:157], v[106:109]
	v_mfma_f32_16x16x32_bf16 v[94:97], v[130:133], v[162:165], v[94:97]
	v_mfma_f32_16x16x32_bf16 v[90:93], v[138:141], v[162:165], v[90:93]
	v_mfma_f32_16x16x32_bf16 v[78:81], v[130:133], v[170:173], v[78:81]
	v_mfma_f32_16x16x32_bf16 v[74:77], v[138:141], v[170:173], v[74:77]
	v_mfma_f32_16x16x32_bf16 v[126:129], v[134:137], v[150:153], v[126:129]
	v_mfma_f32_16x16x32_bf16 v[122:125], v[142:145], v[150:153], v[122:125]
	v_mfma_f32_16x16x32_bf16 v[110:113], v[134:137], v[158:161], v[110:113]
	v_mfma_f32_16x16x32_bf16 v[106:109], v[142:145], v[158:161], v[106:109]
	v_mfma_f32_16x16x32_bf16 v[94:97], v[134:137], v[166:169], v[94:97]
	v_mfma_f32_16x16x32_bf16 v[90:93], v[142:145], v[166:169], v[90:93]
	v_mfma_f32_16x16x32_bf16 v[78:81], v[134:137], v[174:177], v[78:81]
	v_mfma_f32_16x16x32_bf16 v[74:77], v[142:145], v[174:177], v[74:77]
	s_setprio 0
	s_barrier
	s_add_i32 s47, 0, 0x14000
	s_add_i32 s22, s46, s5
	v_add_u32_e32 v206, s47, v191
	v_lshl_add_u64 v[210:211], s[26:27], 0, v[180:181]
	s_mov_b32 m0, s22
	ds_read_b128 v[194:197], v206
	ds_read_b128 v[198:201], v206 offset:1024
	ds_read_b128 v[202:205], v206 offset:2048
	ds_read_b128 v[206:209], v206 offset:3072
	global_load_lds_dwordx4 v[210:211], off
	v_lshl_add_u64 v[220:221], s[26:27], 0, v[178:179]
	s_add_i32 m0, s22, 0x2000
	s_nop 0
	global_load_lds_dwordx4 v[220:221], off
	s_barrier
	s_waitcnt lgkmcnt(0)
	s_setprio 1
	v_mfma_f32_16x16x32_bf16 v[118:121], v[194:197], v[146:149], v[118:121]
	v_mfma_f32_16x16x32_bf16 v[114:117], v[202:205], v[146:149], v[114:117]
	v_mfma_f32_16x16x32_bf16 v[102:105], v[194:197], v[154:157], v[102:105]
	v_mfma_f32_16x16x32_bf16 v[98:101], v[202:205], v[154:157], v[98:101]
	v_mfma_f32_16x16x32_bf16 v[86:89], v[194:197], v[162:165], v[86:89]
	v_mfma_f32_16x16x32_bf16 v[82:85], v[202:205], v[162:165], v[82:85]
	v_mfma_f32_16x16x32_bf16 v[70:73], v[194:197], v[170:173], v[70:73]
	v_mfma_f32_16x16x32_bf16 v[66:69], v[202:205], v[170:173], v[66:69]
	v_mfma_f32_16x16x32_bf16 v[118:121], v[198:201], v[150:153], v[118:121]
	v_mfma_f32_16x16x32_bf16 v[114:117], v[206:209], v[150:153], v[114:117]
	v_mfma_f32_16x16x32_bf16 v[102:105], v[198:201], v[158:161], v[102:105]
	v_mfma_f32_16x16x32_bf16 v[98:101], v[206:209], v[158:161], v[98:101]
	v_mfma_f32_16x16x32_bf16 v[86:89], v[198:201], v[166:169], v[86:89]
	v_mfma_f32_16x16x32_bf16 v[82:85], v[206:209], v[166:169], v[82:85]
	v_mfma_f32_16x16x32_bf16 v[70:73], v[198:201], v[174:177], v[70:73]
	v_mfma_f32_16x16x32_bf16 v[66:69], v[206:209], v[174:177], v[66:69]
	s_setprio 0
	s_mov_b32 m0, s30
	v_lshl_add_u64 v[222:223], s[28:29], 0, v[180:181]
	s_barrier
	ds_read_b128 v[146:149], v212 offset:16384
	ds_read_b128 v[150:153], v212 offset:17408
	ds_read_b128 v[154:157], v212 offset:18432
	ds_read_b128 v[158:161], v212 offset:19456
	ds_read_b128 v[162:165], v212 offset:20480
	ds_read_b128 v[166:169], v212 offset:21504
	ds_read_b128 v[170:173], v212 offset:22528
	ds_read_b128 v[174:177], v212 offset:23552
	global_load_lds_dwordx4 v[222:223], off
	v_lshl_add_u64 v[224:225], s[28:29], 0, v[178:179]
	s_mov_b32 m0, s31
	s_nop 0
	global_load_lds_dwordx4 v[224:225], off
	s_barrier
	s_waitcnt lgkmcnt(0)
	s_setprio 1
	v_mfma_f32_16x16x32_bf16 v[62:65], v[130:133], v[146:149], v[62:65]
	v_mfma_f32_16x16x32_bf16 v[58:61], v[138:141], v[146:149], v[58:61]
	v_mfma_f32_16x16x32_bf16 v[46:49], v[130:133], v[154:157], v[46:49]
	v_mfma_f32_16x16x32_bf16 v[42:45], v[138:141], v[154:157], v[42:45]
	v_mfma_f32_16x16x32_bf16 v[30:33], v[130:133], v[162:165], v[30:33]
	v_mfma_f32_16x16x32_bf16 v[26:29], v[138:141], v[162:165], v[26:29]
	v_mfma_f32_16x16x32_bf16 v[14:17], v[130:133], v[170:173], v[14:17]
	v_mfma_f32_16x16x32_bf16 v[10:13], v[138:141], v[170:173], v[10:13]
	v_mfma_f32_16x16x32_bf16 v[62:65], v[134:137], v[150:153], v[62:65]
	v_mfma_f32_16x16x32_bf16 v[58:61], v[142:145], v[150:153], v[58:61]
	v_mfma_f32_16x16x32_bf16 v[46:49], v[134:137], v[158:161], v[46:49]
	v_mfma_f32_16x16x32_bf16 v[42:45], v[142:145], v[158:161], v[42:45]
	v_mfma_f32_16x16x32_bf16 v[30:33], v[134:137], v[166:169], v[30:33]
	v_mfma_f32_16x16x32_bf16 v[26:29], v[142:145], v[166:169], v[26:29]
	v_mfma_f32_16x16x32_bf16 v[14:17], v[134:137], v[174:177], v[14:17]
	v_mfma_f32_16x16x32_bf16 v[10:13], v[142:145], v[174:177], v[10:13]
	s_setprio 0
	s_barrier
	s_add_u32 s22, s26, 0x80000
	s_addc_u32 s23, s27, 0
	s_add_i32 s46, s47, s5
	v_lshl_add_u64 v[130:131], s[22:23], 0, v[180:181]
	s_mov_b32 m0, s46
	s_nop 0
	global_load_lds_dwordx4 v[130:131], off
	v_lshl_add_u64 v[130:131], s[22:23], 0, v[178:179]
	s_add_i32 m0, s46, 0x2000
	s_nop 0
	global_load_lds_dwordx4 v[130:131], off
	s_waitcnt vmcnt(6)
	s_barrier
	s_setprio 1
	v_mfma_f32_16x16x32_bf16 v[54:57], v[194:197], v[146:149], v[54:57]
	v_mfma_f32_16x16x32_bf16 v[50:53], v[202:205], v[146:149], v[50:53]
	v_mfma_f32_16x16x32_bf16 v[38:41], v[194:197], v[154:157], v[38:41]
	v_mfma_f32_16x16x32_bf16 v[34:37], v[202:205], v[154:157], v[34:37]
	v_mfma_f32_16x16x32_bf16 v[22:25], v[194:197], v[162:165], v[22:25]
	v_mfma_f32_16x16x32_bf16 v[18:21], v[202:205], v[162:165], v[18:21]
	v_mfma_f32_16x16x32_bf16 v[6:9], v[194:197], v[170:173], v[6:9]
	v_mfma_f32_16x16x32_bf16 v[2:5], v[202:205], v[170:173], v[2:5]
	v_mfma_f32_16x16x32_bf16 v[54:57], v[198:201], v[150:153], v[54:57]
	v_mfma_f32_16x16x32_bf16 v[50:53], v[206:209], v[150:153], v[50:53]
	v_mfma_f32_16x16x32_bf16 v[38:41], v[198:201], v[158:161], v[38:41]
	v_mfma_f32_16x16x32_bf16 v[34:37], v[206:209], v[158:161], v[34:37]
	v_mfma_f32_16x16x32_bf16 v[22:25], v[198:201], v[166:169], v[22:25]
	v_mfma_f32_16x16x32_bf16 v[18:21], v[206:209], v[166:169], v[18:21]
	v_mfma_f32_16x16x32_bf16 v[6:9], v[198:201], v[174:177], v[6:9]
	v_mfma_f32_16x16x32_bf16 v[2:5], v[206:209], v[174:177], v[2:5]
	s_setprio 0
	s_add_i32 s46, 0, 0x18000
	v_add_u32_e32 v142, s46, v191
	s_barrier
	ds_read_b128 v[130:133], v142
	ds_read_b128 v[134:137], v142 offset:1024
	ds_read_b128 v[138:141], v142 offset:2048
	ds_read_b128 v[142:145], v142 offset:3072
	s_add_u32 s22, s28, 0x80000
	s_addc_u32 s23, s29, 0
	s_mov_b32 m0, s34
	v_lshl_add_u64 v[194:195], s[22:23], 0, v[180:181]
	ds_read_b128 v[146:149], v212 offset:32768
	ds_read_b128 v[150:153], v212 offset:33792
	ds_read_b128 v[154:157], v212 offset:34816
	ds_read_b128 v[158:161], v212 offset:35840
	ds_read_b128 v[162:165], v212 offset:36864
	ds_read_b128 v[166:169], v212 offset:37888
	ds_read_b128 v[170:173], v212 offset:38912
	ds_read_b128 v[174:177], v212 offset:39936
	global_load_lds_dwordx4 v[194:195], off
	v_lshl_add_u64 v[194:195], s[22:23], 0, v[178:179]
	s_mov_b32 m0, s35
	s_nop 0
	global_load_lds_dwordx4 v[194:195], off
	s_waitcnt lgkmcnt(8)
	s_barrier
	s_waitcnt lgkmcnt(0)
	s_setprio 1
	v_mfma_f32_16x16x32_bf16 v[126:129], v[130:133], v[146:149], v[126:129]
	v_mfma_f32_16x16x32_bf16 v[122:125], v[138:141], v[146:149], v[122:125]
	v_mfma_f32_16x16x32_bf16 v[110:113], v[130:133], v[154:157], v[110:113]
	v_mfma_f32_16x16x32_bf16 v[106:109], v[138:141], v[154:157], v[106:109]
	v_mfma_f32_16x16x32_bf16 v[94:97], v[130:133], v[162:165], v[94:97]
	v_mfma_f32_16x16x32_bf16 v[90:93], v[138:141], v[162:165], v[90:93]
	v_mfma_f32_16x16x32_bf16 v[78:81], v[130:133], v[170:173], v[78:81]
	v_mfma_f32_16x16x32_bf16 v[74:77], v[138:141], v[170:173], v[74:77]
	v_mfma_f32_16x16x32_bf16 v[126:129], v[134:137], v[150:153], v[126:129]
	v_mfma_f32_16x16x32_bf16 v[122:125], v[142:145], v[150:153], v[122:125]
	v_mfma_f32_16x16x32_bf16 v[110:113], v[134:137], v[158:161], v[110:113]
	v_mfma_f32_16x16x32_bf16 v[106:109], v[142:145], v[158:161], v[106:109]
	v_mfma_f32_16x16x32_bf16 v[94:97], v[134:137], v[166:169], v[94:97]
	v_mfma_f32_16x16x32_bf16 v[90:93], v[142:145], v[166:169], v[90:93]
	v_mfma_f32_16x16x32_bf16 v[78:81], v[134:137], v[174:177], v[78:81]
	v_mfma_f32_16x16x32_bf16 v[74:77], v[142:145], v[174:177], v[74:77]
	s_setprio 0
	s_barrier
	s_add_i32 s28, 0, 0x1c000
	s_add_i32 s22, s46, s5
	v_add_u32_e32 v206, s28, v191
	v_lshl_add_u64 v[210:211], v[210:211], 0, s[6:7]
	s_mov_b32 m0, s22
	ds_read_b128 v[194:197], v206
	ds_read_b128 v[198:201], v206 offset:1024
	ds_read_b128 v[202:205], v206 offset:2048
	ds_read_b128 v[206:209], v206 offset:3072
	global_load_lds_dwordx4 v[210:211], off
	v_lshl_add_u64 v[210:211], v[220:221], 0, s[6:7]
	s_add_i32 m0, s22, 0x2000
	s_nop 0
	global_load_lds_dwordx4 v[210:211], off
	s_barrier
	s_waitcnt lgkmcnt(0)
	s_setprio 1
	v_mfma_f32_16x16x32_bf16 v[118:121], v[194:197], v[146:149], v[118:121]
	v_mfma_f32_16x16x32_bf16 v[114:117], v[202:205], v[146:149], v[114:117]
	v_mfma_f32_16x16x32_bf16 v[102:105], v[194:197], v[154:157], v[102:105]
	v_mfma_f32_16x16x32_bf16 v[98:101], v[202:205], v[154:157], v[98:101]
	v_mfma_f32_16x16x32_bf16 v[86:89], v[194:197], v[162:165], v[86:89]
	v_mfma_f32_16x16x32_bf16 v[82:85], v[202:205], v[162:165], v[82:85]
	v_mfma_f32_16x16x32_bf16 v[70:73], v[194:197], v[170:173], v[70:73]
	v_mfma_f32_16x16x32_bf16 v[66:69], v[202:205], v[170:173], v[66:69]
	v_mfma_f32_16x16x32_bf16 v[118:121], v[198:201], v[150:153], v[118:121]
	v_mfma_f32_16x16x32_bf16 v[114:117], v[206:209], v[150:153], v[114:117]
	v_mfma_f32_16x16x32_bf16 v[102:105], v[198:201], v[158:161], v[102:105]
	v_mfma_f32_16x16x32_bf16 v[98:101], v[206:209], v[158:161], v[98:101]
	v_mfma_f32_16x16x32_bf16 v[86:89], v[198:201], v[166:169], v[86:89]
	v_mfma_f32_16x16x32_bf16 v[82:85], v[206:209], v[166:169], v[82:85]
	v_mfma_f32_16x16x32_bf16 v[70:73], v[198:201], v[174:177], v[70:73]
	v_mfma_f32_16x16x32_bf16 v[66:69], v[206:209], v[174:177], v[66:69]
	s_setprio 0
	s_mov_b32 m0, s36
	v_lshl_add_u64 v[210:211], v[222:223], 0, s[6:7]
	s_barrier
	ds_read_b128 v[146:149], v212 offset:49152
	ds_read_b128 v[150:153], v212 offset:50176
	ds_read_b128 v[154:157], v212 offset:51200
	ds_read_b128 v[158:161], v212 offset:52224
	ds_read_b128 v[162:165], v212 offset:53248
	ds_read_b128 v[166:169], v212 offset:54272
	ds_read_b128 v[170:173], v212 offset:55296
	ds_read_b128 v[174:177], v212 offset:56320
	global_load_lds_dwordx4 v[210:211], off
	v_lshl_add_u64 v[210:211], v[224:225], 0, s[6:7]
	s_mov_b32 m0, s37
	s_nop 0
	global_load_lds_dwordx4 v[210:211], off
	s_barrier
	s_waitcnt lgkmcnt(0)
	s_setprio 1
	v_mfma_f32_16x16x32_bf16 v[62:65], v[130:133], v[146:149], v[62:65]
	v_mfma_f32_16x16x32_bf16 v[58:61], v[138:141], v[146:149], v[58:61]
	v_mfma_f32_16x16x32_bf16 v[46:49], v[130:133], v[154:157], v[46:49]
	v_mfma_f32_16x16x32_bf16 v[42:45], v[138:141], v[154:157], v[42:45]
	v_mfma_f32_16x16x32_bf16 v[30:33], v[130:133], v[162:165], v[30:33]
	v_mfma_f32_16x16x32_bf16 v[26:29], v[138:141], v[162:165], v[26:29]
	v_mfma_f32_16x16x32_bf16 v[14:17], v[130:133], v[170:173], v[14:17]
	v_mfma_f32_16x16x32_bf16 v[10:13], v[138:141], v[170:173], v[10:13]
	v_mfma_f32_16x16x32_bf16 v[62:65], v[134:137], v[150:153], v[62:65]
	v_mfma_f32_16x16x32_bf16 v[58:61], v[142:145], v[150:153], v[58:61]
	v_mfma_f32_16x16x32_bf16 v[46:49], v[134:137], v[158:161], v[46:49]
	v_mfma_f32_16x16x32_bf16 v[42:45], v[142:145], v[158:161], v[42:45]
	v_mfma_f32_16x16x32_bf16 v[30:33], v[134:137], v[166:169], v[30:33]
	v_mfma_f32_16x16x32_bf16 v[26:29], v[142:145], v[166:169], v[26:29]
	v_mfma_f32_16x16x32_bf16 v[14:17], v[134:137], v[174:177], v[14:17]
	v_mfma_f32_16x16x32_bf16 v[10:13], v[142:145], v[174:177], v[10:13]
	s_setprio 0
	s_barrier
	s_add_u32 s22, s26, 0x80080
	s_addc_u32 s23, s27, 0
	s_add_i32 s26, s28, s5
	v_lshl_add_u64 v[130:131], s[22:23], 0, v[180:181]
	s_mov_b32 m0, s26
	s_nop 0
	global_load_lds_dwordx4 v[130:131], off
	v_lshl_add_u64 v[130:131], s[22:23], 0, v[178:179]
	s_add_i32 m0, s26, 0x2000
	s_nop 0
	global_load_lds_dwordx4 v[130:131], off
	s_waitcnt vmcnt(6)
	s_barrier
	s_setprio 1
	v_mfma_f32_16x16x32_bf16 v[54:57], v[194:197], v[146:149], v[54:57]
	v_mfma_f32_16x16x32_bf16 v[50:53], v[202:205], v[146:149], v[50:53]
	v_mfma_f32_16x16x32_bf16 v[38:41], v[194:197], v[154:157], v[38:41]
	v_mfma_f32_16x16x32_bf16 v[34:37], v[202:205], v[154:157], v[34:37]
	v_mfma_f32_16x16x32_bf16 v[22:25], v[194:197], v[162:165], v[22:25]
	v_mfma_f32_16x16x32_bf16 v[18:21], v[202:205], v[162:165], v[18:21]
	v_mfma_f32_16x16x32_bf16 v[6:9], v[194:197], v[170:173], v[6:9]
	v_mfma_f32_16x16x32_bf16 v[2:5], v[202:205], v[170:173], v[2:5]
	v_mfma_f32_16x16x32_bf16 v[54:57], v[198:201], v[150:153], v[54:57]
	v_mfma_f32_16x16x32_bf16 v[50:53], v[206:209], v[150:153], v[50:53]
	v_mfma_f32_16x16x32_bf16 v[38:41], v[198:201], v[158:161], v[38:41]
	v_mfma_f32_16x16x32_bf16 v[34:37], v[206:209], v[158:161], v[34:37]
	v_mfma_f32_16x16x32_bf16 v[22:25], v[198:201], v[166:169], v[22:25]
	v_mfma_f32_16x16x32_bf16 v[18:21], v[206:209], v[166:169], v[18:21]
	v_mfma_f32_16x16x32_bf16 v[6:9], v[198:201], v[174:177], v[6:9]
	v_mfma_f32_16x16x32_bf16 v[2:5], v[206:209], v[174:177], v[2:5]
	s_setprio 0
	s_add_i32 s45, s45, 2
	s_add_u32 s43, s43, 0x100
	s_addc_u32 s44, s44, 0
	s_cmp_gt_u32 s45, 29
	s_mov_b64 s[22:23], s[24:25]
	s_barrier
	s_cbranch_scc0 .LBB0_253
	s_nop 0
	s_nop 0
	s_nop 0
	s_nop 0
	s_nop 0
	s_nop 0
	v_lshl_add_u32 v196, s39, 8, v1
	v_lshl_or_b32 v194, s40, 8, v192
	v_readlane_b32 s24, v254, 46
	v_ashrrev_i32_e32 v195, 31, v194
	v_ashrrev_i32_e32 v197, 31, v196
	v_readlane_b32 s25, v254, 47
	v_or_b32_e32 v210, 16, v196
	v_lshlrev_b64 v[130:131], 13, v[196:197]
	v_lshl_add_u64 v[198:199], v[194:195], 2, s[24:25]
	v_or_b32_e32 v206, 32, v196
	v_or_b32_e32 v202, 48, v196
	v_ashrrev_i32_e32 v211, 31, v210
	v_lshl_add_u64 v[224:225], v[198:199], 0, v[130:131]
	v_ashrrev_i32_e32 v207, 31, v206
	v_ashrrev_i32_e32 v203, 31, v202
	v_lshlrev_b64 v[130:131], 13, v[210:211]
	global_load_dwordx4 v[220:223], v[224:225], off
	global_load_dwordx4 v[236:239], v[224:225], off offset:64
	global_load_dwordx4 v[240:243], v[224:225], off offset:512
	global_load_dwordx4 v[244:247], v[224:225], off offset:576
	v_lshlrev_b64 v[132:133], 13, v[206:207]
	v_lshlrev_b64 v[134:135], 13, v[202:203]
	v_lshl_add_u64 v[208:209], v[198:199], 0, v[130:131]
	v_lshl_add_u64 v[204:205], v[198:199], 0, v[132:133]
	v_lshl_add_u64 v[200:201], v[198:199], 0, v[134:135]
	global_load_dwordx4 v[174:177], v[208:209], off
	global_load_dwordx4 v[170:173], v[208:209], off offset:64
	global_load_dwordx4 v[166:169], v[208:209], off offset:512
	global_load_dwordx4 v[162:165], v[208:209], off offset:576
	global_load_dwordx4 v[158:161], v[204:205], off
	global_load_dwordx4 v[154:157], v[204:205], off offset:64
	global_load_dwordx4 v[150:153], v[204:205], off offset:512
	global_load_dwordx4 v[146:149], v[204:205], off offset:576
	global_load_dwordx4 v[142:145], v[200:201], off
	global_load_dwordx4 v[138:141], v[200:201], off offset:64
	global_load_dwordx4 v[134:137], v[200:201], off offset:512
	global_load_dwordx4 v[130:133], v[200:201], off offset:576
	v_lshlrev_b64 v[248:249], 11, v[196:197]
	v_readlane_b32 s22, v252, 5
	v_lshl_add_u64 v[248:249], v[248:249], 0, v[194:195]
	v_readlane_b32 s23, v252, 6
	v_readlane_b32 s26, v254, 48
	v_readlane_b32 s27, v254, 49
	v_lshl_add_u64 v[248:249], v[248:249], 1, s[22:23]
	v_readlane_b32 s22, v252, 40
	v_readlane_b32 s23, v252, 41
	s_waitcnt vmcnt(0)
	v_pk_add_f32 v[128:129], v[128:129], v[222:223]
	v_pk_add_f32 v[126:127], v[126:127], v[220:221]
	v_pk_add_f32 v[122:123], v[122:123], v[236:237]
	v_pk_add_f32 v[118:119], v[118:119], v[240:241]
	global_store_dwordx4 v[224:225], v[126:129], off
	v_cvt_pk_bf16_f32 v220, v126, v127
	v_mul_f32_e32 v213, v123, v123
	v_mul_f32_e32 v127, v127, v127
	v_pk_add_f32 v[124:125], v[124:125], v[238:239]
	v_pk_add_f32 v[114:115], v[114:115], v[244:245]
	v_mul_f32_e32 v226, v119, v119
	v_fmac_f32_e32 v127, v126, v126
	v_fmac_f32_e32 v213, v122, v122
	v_pk_add_f32 v[120:121], v[120:121], v[242:243]
	v_mul_f32_e32 v235, v115, v115
	v_fmac_f32_e32 v226, v118, v118
	v_fmac_f32_e32 v127, v128, v128
	v_fmac_f32_e32 v213, v124, v124
	v_pk_add_f32 v[116:117], v[116:117], v[246:247]
	v_cvt_pk_bf16_f32 v221, v128, v129
	v_fmac_f32_e32 v235, v114, v114
	v_fmac_f32_e32 v226, v120, v120
	v_fmac_f32_e32 v127, v129, v129
	v_fmac_f32_e32 v213, v125, v125
	v_cvt_pk_bf16_f32 v222, v122, v123
	v_cvt_pk_bf16_f32 v223, v124, v125
	v_cvt_pk_bf16_f32 v236, v118, v119
	v_cvt_pk_bf16_f32 v237, v120, v121
	v_cvt_pk_bf16_f32 v238, v114, v115
	v_cvt_pk_bf16_f32 v239, v116, v117
	global_store_dwordx2 v[248:249], v[220:221], off
	global_store_dwordx4 v[224:225], v[122:125], off offset:64
	global_store_dwordx2 v[248:249], v[222:223], off offset:32
	global_store_dwordx4 v[224:225], v[118:121], off offset:512
	global_store_dwordx2 v[248:249], v[236:237], off offset:256
	global_store_dwordx4 v[224:225], v[114:117], off offset:576
	global_store_dwordx2 v[248:249], v[238:239], off offset:288
	v_fmac_f32_e32 v235, v116, v116
	v_fmac_f32_e32 v226, v121, v121
	v_add_f32_e32 v114, v127, v213
	v_fmac_f32_e32 v235, v117, v117
	v_add_f32_e32 v114, v114, v226
	v_add_f32_e32 v114, v114, v235
	v_mov_b32_e32 v115, v114
	s_nop 1
	v_permlane32_swap_b32_e32 v114, v115
	v_add_f32_e32 v116, v114, v115
	v_mov_b32_e32 v117, v116
	s_nop 1
	v_permlane16_swap_b32_e32 v116, v117
	v_lshl_add_u64 v[114:115], v[196:197], 2, s[22:23]
	s_and_saveexec_b64 s[22:23], s[10:11]
	s_cbranch_execz .LBB0_256
	v_add_f32_e32 v116, v116, v117
	global_atomic_add_f32 v[114:115], v116, off

.LBB0_383:
	s_add_u32 s14, s12, 0xfff80080
	s_addc_u32 s15, s13, -1
	s_add_i32 s43, 0, 0x10000
	v_add_u32_e32 v142, s43, v144
	ds_read_b128 v[162:165], v142
	ds_read_b128 v[166:169], v142 offset:1024
	ds_read_b128 v[170:173], v142 offset:2048
	ds_read_b128 v[174:177], v142 offset:3072
	s_cmp_eq_u32 s42, 28
	s_cselect_b32 s25, s4, s15
	s_cselect_b32 s24, s19, s14
	s_cselect_b32 s15, s17, s41
	s_cselect_b32 s14, s39, s40
	v_lshl_add_u64 v[142:143], s[12:13], 0, v[138:139]
	s_add_i32 m0, s29, 0xc000
	ds_read_b128 v[178:181], v161
	ds_read_b128 v[182:185], v161 offset:1024
	ds_read_b128 v[194:197], v161 offset:2048
	ds_read_b128 v[198:201], v161 offset:3072
	ds_read_b128 v[202:205], v161 offset:4096
	ds_read_b128 v[206:209], v161 offset:5120
	ds_read_b128 v[210:213], v161 offset:6144
	ds_read_b128 v[236:239], v161 offset:7168
	global_load_lds_dwordx4 v[142:143], off
	v_lshl_add_u64 v[142:143], s[12:13], 0, v[140:141]
	s_add_i32 m0, s29, 0xe000
	s_nop 0
	global_load_lds_dwordx4 v[142:143], off
	s_waitcnt lgkmcnt(8)
	s_barrier
	s_waitcnt lgkmcnt(0)
	s_setprio 1
	v_mfma_f32_16x16x32_bf16 v[126:129], v[162:165], v[178:181], v[126:129]
	v_mfma_f32_16x16x32_bf16 v[122:125], v[170:173], v[178:181], v[122:125]
	v_mfma_f32_16x16x32_bf16 v[110:113], v[162:165], v[194:197], v[110:113]
	v_mfma_f32_16x16x32_bf16 v[106:109], v[170:173], v[194:197], v[106:109]
	v_mfma_f32_16x16x32_bf16 v[94:97], v[162:165], v[202:205], v[94:97]
	v_mfma_f32_16x16x32_bf16 v[90:93], v[170:173], v[202:205], v[90:93]
	v_mfma_f32_16x16x32_bf16 v[78:81], v[162:165], v[210:213], v[78:81]
	v_mfma_f32_16x16x32_bf16 v[74:77], v[170:173], v[210:213], v[74:77]
	v_mfma_f32_16x16x32_bf16 v[126:129], v[166:169], v[182:185], v[126:129]
	v_mfma_f32_16x16x32_bf16 v[122:125], v[174:177], v[182:185], v[122:125]
	v_mfma_f32_16x16x32_bf16 v[110:113], v[166:169], v[198:201], v[110:113]
	v_mfma_f32_16x16x32_bf16 v[106:109], v[174:177], v[198:201], v[106:109]
	v_mfma_f32_16x16x32_bf16 v[94:97], v[166:169], v[206:209], v[94:97]
	v_mfma_f32_16x16x32_bf16 v[90:93], v[174:177], v[206:209], v[90:93]
	v_mfma_f32_16x16x32_bf16 v[78:81], v[166:169], v[236:239], v[78:81]
	v_mfma_f32_16x16x32_bf16 v[74:77], v[174:177], v[236:239], v[74:77]
	s_setprio 0
	s_barrier
	s_add_i32 s46, 0, 0x14000
	v_add_u32_e32 v142, s46, v144
	s_add_i32 s43, s43, s28
	ds_read_b128 v[240:243], v142
	ds_read_b128 v[244:247], v142 offset:1024
	ds_read_b128 v[248:251], v142 offset:2048
	ds_read_b128 v[220:223], v142 offset:3072
	v_lshl_add_u64 v[142:143], s[14:15], 0, v[134:135]
	s_mov_b32 m0, s43
	v_lshl_add_u64 v[224:225], s[14:15], 0, v[130:131]
	global_load_lds_dwordx4 v[142:143], off
	s_add_i32 m0, s43, 0x2000
	s_nop 0
	global_load_lds_dwordx4 v[224:225], off
	s_barrier
	s_waitcnt lgkmcnt(0)
	s_setprio 1
	v_mfma_f32_16x16x32_bf16 v[118:121], v[240:243], v[178:181], v[118:121]
	v_mfma_f32_16x16x32_bf16 v[114:117], v[248:251], v[178:181], v[114:117]
	v_mfma_f32_16x16x32_bf16 v[102:105], v[240:243], v[194:197], v[102:105]
	v_mfma_f32_16x16x32_bf16 v[98:101], v[248:251], v[194:197], v[98:101]
	v_mfma_f32_16x16x32_bf16 v[86:89], v[240:243], v[202:205], v[86:89]
	v_mfma_f32_16x16x32_bf16 v[82:85], v[248:251], v[202:205], v[82:85]
	v_mfma_f32_16x16x32_bf16 v[70:73], v[240:243], v[210:213], v[70:73]
	v_mfma_f32_16x16x32_bf16 v[66:69], v[248:251], v[210:213], v[66:69]
	v_mfma_f32_16x16x32_bf16 v[118:121], v[244:247], v[182:185], v[118:121]
	v_mfma_f32_16x16x32_bf16 v[114:117], v[220:223], v[182:185], v[114:117]
	v_mfma_f32_16x16x32_bf16 v[102:105], v[244:247], v[198:201], v[102:105]
	v_mfma_f32_16x16x32_bf16 v[98:101], v[220:223], v[198:201], v[98:101]
	v_mfma_f32_16x16x32_bf16 v[86:89], v[244:247], v[206:209], v[86:89]
	v_mfma_f32_16x16x32_bf16 v[82:85], v[220:223], v[206:209], v[82:85]
	v_mfma_f32_16x16x32_bf16 v[70:73], v[244:247], v[236:239], v[70:73]
	v_mfma_f32_16x16x32_bf16 v[66:69], v[220:223], v[236:239], v[66:69]
	s_setprio 0
	s_mov_b32 m0, s29
	v_lshl_add_u64 v[146:147], s[24:25], 0, v[136:137]
	s_barrier
	ds_read_b128 v[178:181], v161 offset:16384
	ds_read_b128 v[182:185], v161 offset:17408
	ds_read_b128 v[194:197], v161 offset:18432
	ds_read_b128 v[198:201], v161 offset:19456
	ds_read_b128 v[202:205], v161 offset:20480
	ds_read_b128 v[206:209], v161 offset:21504
	ds_read_b128 v[210:213], v161 offset:22528
	ds_read_b128 v[236:239], v161 offset:23552
	global_load_lds_dwordx4 v[146:147], off
	v_lshl_add_u64 v[148:149], s[24:25], 0, v[132:133]
	s_mov_b32 m0, s30
	s_nop 0
	global_load_lds_dwordx4 v[148:149], off
	s_barrier
	s_waitcnt lgkmcnt(0)
	s_setprio 1
	v_mfma_f32_16x16x32_bf16 v[62:65], v[162:165], v[178:181], v[62:65]
	v_mfma_f32_16x16x32_bf16 v[58:61], v[170:173], v[178:181], v[58:61]
	v_mfma_f32_16x16x32_bf16 v[46:49], v[162:165], v[194:197], v[46:49]
	v_mfma_f32_16x16x32_bf16 v[42:45], v[170:173], v[194:197], v[42:45]
	v_mfma_f32_16x16x32_bf16 v[30:33], v[162:165], v[202:205], v[30:33]
	v_mfma_f32_16x16x32_bf16 v[26:29], v[170:173], v[202:205], v[26:29]
	v_mfma_f32_16x16x32_bf16 v[14:17], v[162:165], v[210:213], v[14:17]
	v_mfma_f32_16x16x32_bf16 v[10:13], v[170:173], v[210:213], v[10:13]
	v_mfma_f32_16x16x32_bf16 v[62:65], v[166:169], v[182:185], v[62:65]
	v_mfma_f32_16x16x32_bf16 v[58:61], v[174:177], v[182:185], v[58:61]
	v_mfma_f32_16x16x32_bf16 v[46:49], v[166:169], v[198:201], v[46:49]
	v_mfma_f32_16x16x32_bf16 v[42:45], v[174:177], v[198:201], v[42:45]
	v_mfma_f32_16x16x32_bf16 v[30:33], v[166:169], v[206:209], v[30:33]
	v_mfma_f32_16x16x32_bf16 v[26:29], v[174:177], v[206:209], v[26:29]
	v_mfma_f32_16x16x32_bf16 v[14:17], v[166:169], v[236:239], v[14:17]
	v_mfma_f32_16x16x32_bf16 v[10:13], v[174:177], v[236:239], v[10:13]
	s_setprio 0
	s_barrier
	s_add_u32 s44, s14, 0x80000
	s_addc_u32 s45, s15, 0
	s_add_i32 s43, s46, s28
	v_lshl_add_u64 v[162:163], s[44:45], 0, v[134:135]
	s_mov_b32 m0, s43
	s_nop 0
	global_load_lds_dwordx4 v[162:163], off
	v_lshl_add_u64 v[162:163], s[44:45], 0, v[130:131]
	s_add_i32 m0, s43, 0x2000
	s_nop 0
	global_load_lds_dwordx4 v[162:163], off
	s_waitcnt vmcnt(6)
	s_barrier
	s_setprio 1
	v_mfma_f32_16x16x32_bf16 v[54:57], v[240:243], v[178:181], v[54:57]
	v_mfma_f32_16x16x32_bf16 v[50:53], v[248:251], v[178:181], v[50:53]
	v_mfma_f32_16x16x32_bf16 v[38:41], v[240:243], v[194:197], v[38:41]
	v_mfma_f32_16x16x32_bf16 v[34:37], v[248:251], v[194:197], v[34:37]
	v_mfma_f32_16x16x32_bf16 v[22:25], v[240:243], v[202:205], v[22:25]
	v_mfma_f32_16x16x32_bf16 v[18:21], v[248:251], v[202:205], v[18:21]
	v_mfma_f32_16x16x32_bf16 v[6:9], v[240:243], v[210:213], v[6:9]
	v_mfma_f32_16x16x32_bf16 v[2:5], v[248:251], v[210:213], v[2:5]
	v_mfma_f32_16x16x32_bf16 v[54:57], v[244:247], v[182:185], v[54:57]
	v_mfma_f32_16x16x32_bf16 v[50:53], v[220:223], v[182:185], v[50:53]
	v_mfma_f32_16x16x32_bf16 v[38:41], v[244:247], v[198:201], v[38:41]
	v_mfma_f32_16x16x32_bf16 v[34:37], v[220:223], v[198:201], v[34:37]
	v_mfma_f32_16x16x32_bf16 v[22:25], v[244:247], v[206:209], v[22:25]
	v_mfma_f32_16x16x32_bf16 v[18:21], v[220:223], v[206:209], v[18:21]
	v_mfma_f32_16x16x32_bf16 v[6:9], v[244:247], v[236:239], v[6:9]
	v_mfma_f32_16x16x32_bf16 v[2:5], v[220:223], v[236:239], v[2:5]
	s_setprio 0
	s_add_i32 s43, 0, 0x18000
	v_add_u32_e32 v174, s43, v144
	s_barrier
	ds_read_b128 v[162:165], v174
	ds_read_b128 v[166:169], v174 offset:1024
	ds_read_b128 v[170:173], v174 offset:2048
	ds_read_b128 v[174:177], v174 offset:3072
	s_add_u32 s24, s24, 0x80000
	s_addc_u32 s25, s25, 0
	s_mov_b32 m0, s31
	v_lshl_add_u64 v[236:237], s[24:25], 0, v[136:137]
	ds_read_b128 v[178:181], v161 offset:32768
	ds_read_b128 v[182:185], v161 offset:33792
	ds_read_b128 v[194:197], v161 offset:34816
	ds_read_b128 v[198:201], v161 offset:35840
	ds_read_b128 v[202:205], v161 offset:36864
	ds_read_b128 v[206:209], v161 offset:37888
	ds_read_b128 v[210:213], v161 offset:38912
	ds_read_b128 v[220:223], v161 offset:39936
	global_load_lds_dwordx4 v[236:237], off
	v_lshl_add_u64 v[236:237], s[24:25], 0, v[132:133]
	s_mov_b32 m0, s34
	s_nop 0
	global_load_lds_dwordx4 v[236:237], off
	s_waitcnt lgkmcnt(8)
	s_barrier
	s_waitcnt lgkmcnt(0)
	s_setprio 1
	v_mfma_f32_16x16x32_bf16 v[126:129], v[162:165], v[178:181], v[126:129]
	v_mfma_f32_16x16x32_bf16 v[122:125], v[170:173], v[178:181], v[122:125]
	v_mfma_f32_16x16x32_bf16 v[110:113], v[162:165], v[194:197], v[110:113]
	v_mfma_f32_16x16x32_bf16 v[106:109], v[170:173], v[194:197], v[106:109]
	v_mfma_f32_16x16x32_bf16 v[94:97], v[162:165], v[202:205], v[94:97]
	v_mfma_f32_16x16x32_bf16 v[90:93], v[170:173], v[202:205], v[90:93]
	v_mfma_f32_16x16x32_bf16 v[78:81], v[162:165], v[210:213], v[78:81]
	v_mfma_f32_16x16x32_bf16 v[74:77], v[170:173], v[210:213], v[74:77]
	v_mfma_f32_16x16x32_bf16 v[126:129], v[166:169], v[182:185], v[126:129]
	v_mfma_f32_16x16x32_bf16 v[122:125], v[174:177], v[182:185], v[122:125]
	v_mfma_f32_16x16x32_bf16 v[110:113], v[166:169], v[198:201], v[110:113]
	v_mfma_f32_16x16x32_bf16 v[106:109], v[174:177], v[198:201], v[106:109]
	v_mfma_f32_16x16x32_bf16 v[94:97], v[166:169], v[206:209], v[94:97]
	v_mfma_f32_16x16x32_bf16 v[90:93], v[174:177], v[206:209], v[90:93]
	v_mfma_f32_16x16x32_bf16 v[78:81], v[166:169], v[220:223], v[78:81]
	v_mfma_f32_16x16x32_bf16 v[74:77], v[174:177], v[220:223], v[74:77]
	s_setprio 0
	s_barrier
	s_add_i32 s24, 0, 0x1c000
	s_add_i32 s25, s43, s28
	v_add_u32_e32 v248, s24, v144
	v_lshl_add_u64 v[142:143], v[142:143], 0, s[6:7]
	s_mov_b32 m0, s25
	ds_read_b128 v[236:239], v248
	ds_read_b128 v[240:243], v248 offset:1024
	ds_read_b128 v[244:247], v248 offset:2048
	ds_read_b128 v[248:251], v248 offset:3072
	global_load_lds_dwordx4 v[142:143], off
	v_lshl_add_u64 v[142:143], v[224:225], 0, s[6:7]
	s_add_i32 m0, s25, 0x2000
	s_nop 0
	global_load_lds_dwordx4 v[142:143], off
	s_barrier
	s_waitcnt lgkmcnt(0)
	s_setprio 1
	v_mfma_f32_16x16x32_bf16 v[118:121], v[236:239], v[178:181], v[118:121]
	v_mfma_f32_16x16x32_bf16 v[114:117], v[244:247], v[178:181], v[114:117]
	v_mfma_f32_16x16x32_bf16 v[102:105], v[236:239], v[194:197], v[102:105]
	v_mfma_f32_16x16x32_bf16 v[98:101], v[244:247], v[194:197], v[98:101]
	v_mfma_f32_16x16x32_bf16 v[86:89], v[236:239], v[202:205], v[86:89]
	v_mfma_f32_16x16x32_bf16 v[82:85], v[244:247], v[202:205], v[82:85]
	v_mfma_f32_16x16x32_bf16 v[70:73], v[236:239], v[210:213], v[70:73]
	v_mfma_f32_16x16x32_bf16 v[66:69], v[244:247], v[210:213], v[66:69]
	v_mfma_f32_16x16x32_bf16 v[118:121], v[240:243], v[182:185], v[118:121]
	v_mfma_f32_16x16x32_bf16 v[114:117], v[248:251], v[182:185], v[114:117]
	v_mfma_f32_16x16x32_bf16 v[102:105], v[240:243], v[198:201], v[102:105]
	v_mfma_f32_16x16x32_bf16 v[98:101], v[248:251], v[198:201], v[98:101]
	v_mfma_f32_16x16x32_bf16 v[86:89], v[240:243], v[206:209], v[86:89]
	v_mfma_f32_16x16x32_bf16 v[82:85], v[248:251], v[206:209], v[82:85]
	v_mfma_f32_16x16x32_bf16 v[70:73], v[240:243], v[220:223], v[70:73]
	v_mfma_f32_16x16x32_bf16 v[66:69], v[248:251], v[220:223], v[66:69]
	s_setprio 0
	s_mov_b32 m0, s35
	v_lshl_add_u64 v[142:143], v[146:147], 0, s[6:7]
	s_barrier
	ds_read_b128 v[178:181], v161 offset:49152
	ds_read_b128 v[182:185], v161 offset:50176
	ds_read_b128 v[194:197], v161 offset:51200
	ds_read_b128 v[198:201], v161 offset:52224
	ds_read_b128 v[202:205], v161 offset:53248
	ds_read_b128 v[206:209], v161 offset:54272
	ds_read_b128 v[210:213], v161 offset:55296
	ds_read_b128 v[220:223], v161 offset:56320
	global_load_lds_dwordx4 v[142:143], off
	v_lshl_add_u64 v[142:143], v[148:149], 0, s[6:7]
	s_mov_b32 m0, s36
	s_nop 0
	global_load_lds_dwordx4 v[142:143], off
	s_barrier
	s_waitcnt lgkmcnt(0)
	s_setprio 1
	v_mfma_f32_16x16x32_bf16 v[62:65], v[162:165], v[178:181], v[62:65]
	v_mfma_f32_16x16x32_bf16 v[58:61], v[170:173], v[178:181], v[58:61]
	v_mfma_f32_16x16x32_bf16 v[46:49], v[162:165], v[194:197], v[46:49]
	v_mfma_f32_16x16x32_bf16 v[42:45], v[170:173], v[194:197], v[42:45]
	v_mfma_f32_16x16x32_bf16 v[30:33], v[162:165], v[202:205], v[30:33]
	v_mfma_f32_16x16x32_bf16 v[26:29], v[170:173], v[202:205], v[26:29]
	v_mfma_f32_16x16x32_bf16 v[14:17], v[162:165], v[210:213], v[14:17]
	v_mfma_f32_16x16x32_bf16 v[10:13], v[170:173], v[210:213], v[10:13]
	v_mfma_f32_16x16x32_bf16 v[62:65], v[166:169], v[182:185], v[62:65]
	v_mfma_f32_16x16x32_bf16 v[58:61], v[174:177], v[182:185], v[58:61]
	v_mfma_f32_16x16x32_bf16 v[46:49], v[166:169], v[198:201], v[46:49]
	v_mfma_f32_16x16x32_bf16 v[42:45], v[174:177], v[198:201], v[42:45]
	v_mfma_f32_16x16x32_bf16 v[30:33], v[166:169], v[206:209], v[30:33]
	v_mfma_f32_16x16x32_bf16 v[26:29], v[174:177], v[206:209], v[26:29]
	v_mfma_f32_16x16x32_bf16 v[14:17], v[166:169], v[220:223], v[14:17]
	v_mfma_f32_16x16x32_bf16 v[10:13], v[174:177], v[220:223], v[10:13]
	s_setprio 0
	s_barrier
	s_add_u32 s14, s14, 0x80080
	s_addc_u32 s15, s15, 0
	s_add_i32 s24, s24, s28
	v_lshl_add_u64 v[142:143], s[14:15], 0, v[134:135]
	s_mov_b32 m0, s24
	s_nop 0
	global_load_lds_dwordx4 v[142:143], off
	v_lshl_add_u64 v[142:143], s[14:15], 0, v[130:131]
	s_add_i32 m0, s24, 0x2000
	s_nop 0
	global_load_lds_dwordx4 v[142:143], off
	s_waitcnt vmcnt(6)
	s_barrier
	s_setprio 1
	v_mfma_f32_16x16x32_bf16 v[54:57], v[236:239], v[178:181], v[54:57]
	v_mfma_f32_16x16x32_bf16 v[50:53], v[244:247], v[178:181], v[50:53]
	v_mfma_f32_16x16x32_bf16 v[38:41], v[236:239], v[194:197], v[38:41]
	v_mfma_f32_16x16x32_bf16 v[34:37], v[244:247], v[194:197], v[34:37]
	v_mfma_f32_16x16x32_bf16 v[22:25], v[236:239], v[202:205], v[22:25]
	v_mfma_f32_16x16x32_bf16 v[18:21], v[244:247], v[202:205], v[18:21]
	v_mfma_f32_16x16x32_bf16 v[6:9], v[236:239], v[210:213], v[6:9]
	v_mfma_f32_16x16x32_bf16 v[2:5], v[244:247], v[210:213], v[2:5]
	v_mfma_f32_16x16x32_bf16 v[54:57], v[240:243], v[182:185], v[54:57]
	v_mfma_f32_16x16x32_bf16 v[50:53], v[248:251], v[182:185], v[50:53]
	v_mfma_f32_16x16x32_bf16 v[38:41], v[240:243], v[198:201], v[38:41]
	v_mfma_f32_16x16x32_bf16 v[34:37], v[248:251], v[198:201], v[34:37]
	v_mfma_f32_16x16x32_bf16 v[22:25], v[240:243], v[206:209], v[22:25]
	v_mfma_f32_16x16x32_bf16 v[18:21], v[248:251], v[206:209], v[18:21]
	v_mfma_f32_16x16x32_bf16 v[6:9], v[240:243], v[220:223], v[6:9]
	v_mfma_f32_16x16x32_bf16 v[2:5], v[248:251], v[220:223], v[2:5]
	s_setprio 0
	s_add_i32 s42, s42, 2
	s_add_u32 s12, s12, 0x100
	s_addc_u32 s13, s13, 0
	s_add_u32 s40, s40, 0x100
	s_addc_u32 s41, s41, 0
	s_cmp_gt_u32 s42, 29
	s_barrier
	s_cbranch_scc0 .LBB0_383
	s_nop 0
	s_nop 0
	s_nop 0
	s_nop 0
	s_nop 0
	s_nop 0
	s_lshl_b32 s4, s38, 8
	s_cmp_lg_u32 s38, s26
	v_add_u32_e32 v142, s4, v1
	s_cselect_b64 s[24:25], -1, 0
	s_mov_b64 s[12:13], -1
	s_and_b64 vcc, exec, s[24:25]
	v_ashrrev_i32_e32 v143, 31, v142
	s_cbranch_vccz .LBB0_386
	v_readlane_b32 s12, v252, 46
	v_readlane_b32 s13, v252, 47
	s_nop 1
	v_lshl_add_u64 v[162:163], v[142:143], 2, s[12:13]
	global_load_dword v146, v[162:163], off
	s_mov_b64 s[12:13], 0
	s_waitcnt vmcnt(0)
	v_fmamk_f32 v146, v146, 0x3a000000, v215
	v_mul_f32_e32 v147, 0x4b800000, v146
	v_cmp_gt_f32_e32 vcc, s65, v146
	s_nop 1
	v_cndmask_b32_e32 v146, v146, v147, vcc
	v_rsq_f32_e32 v146, v146
	s_nop 0
	v_mul_f32_e32 v147, 0x45800000, v146
	v_cndmask_b32_e32 v162, v146, v147, vcc

.LBB0_695:
	s_add_u32 s24, s22, 0x100
	s_addc_u32 s25, s23, 0
	s_add_i32 s48, 0, 0x10000
	v_add_u32_e32 v142, s48, v191
	ds_read_b128 v[130:133], v142
	ds_read_b128 v[134:137], v142 offset:1024
	ds_read_b128 v[138:141], v142 offset:2048
	ds_read_b128 v[142:145], v142 offset:3072
	s_cmpk_eq_i32 s47, 0x54
	s_cselect_b32 s29, s15, s25
	s_cselect_b32 s28, s14, s24
	s_cselect_b32 s27, s17, s46
	s_cselect_b32 s26, s16, s45
	v_lshl_add_u64 v[178:179], s[22:23], 0, v[198:199]
	s_add_i32 m0, s34, 0xc000
	ds_read_b128 v[146:149], v236
	ds_read_b128 v[150:153], v236 offset:1024
	ds_read_b128 v[154:157], v236 offset:2048
	ds_read_b128 v[158:161], v236 offset:3072
	ds_read_b128 v[162:165], v236 offset:4096
	ds_read_b128 v[166:169], v236 offset:5120
	ds_read_b128 v[170:173], v236 offset:6144
	ds_read_b128 v[174:177], v236 offset:7168
	global_load_lds_dwordx4 v[178:179], off
	v_lshl_add_u64 v[178:179], s[22:23], 0, v[200:201]
	s_add_i32 m0, s34, 0xe000
	s_nop 0
	global_load_lds_dwordx4 v[178:179], off
	s_waitcnt lgkmcnt(8)
	s_barrier
	s_waitcnt lgkmcnt(0)
	s_setprio 1
	v_mfma_f32_16x16x32_bf16 v[126:129], v[130:133], v[146:149], v[126:129]
	v_mfma_f32_16x16x32_bf16 v[122:125], v[138:141], v[146:149], v[122:125]
	v_mfma_f32_16x16x32_bf16 v[110:113], v[130:133], v[154:157], v[110:113]
	v_mfma_f32_16x16x32_bf16 v[106:109], v[138:141], v[154:157], v[106:109]
	v_mfma_f32_16x16x32_bf16 v[94:97], v[130:133], v[162:165], v[94:97]
	v_mfma_f32_16x16x32_bf16 v[90:93], v[138:141], v[162:165], v[90:93]
	v_mfma_f32_16x16x32_bf16 v[78:81], v[130:133], v[170:173], v[78:81]
	v_mfma_f32_16x16x32_bf16 v[74:77], v[138:141], v[170:173], v[74:77]
	v_mfma_f32_16x16x32_bf16 v[126:129], v[134:137], v[150:153], v[126:129]
	v_mfma_f32_16x16x32_bf16 v[122:125], v[142:145], v[150:153], v[122:125]
	v_mfma_f32_16x16x32_bf16 v[110:113], v[134:137], v[158:161], v[110:113]
	v_mfma_f32_16x16x32_bf16 v[106:109], v[142:145], v[158:161], v[106:109]
	v_mfma_f32_16x16x32_bf16 v[94:97], v[134:137], v[166:169], v[94:97]
	v_mfma_f32_16x16x32_bf16 v[90:93], v[142:145], v[166:169], v[90:93]
	v_mfma_f32_16x16x32_bf16 v[78:81], v[134:137], v[174:177], v[78:81]
	v_mfma_f32_16x16x32_bf16 v[74:77], v[142:145], v[174:177], v[74:77]
	s_setprio 0
	s_barrier
	s_add_i32 s49, 0, 0x14000
	s_add_i32 s22, s48, s5
	v_add_u32_e32 v206, s49, v191
	v_lshl_add_u64 v[210:211], s[26:27], 0, v[196:197]
	s_mov_b32 m0, s22
	ds_read_b128 v[178:181], v206
	ds_read_b128 v[182:185], v206 offset:1024
	ds_read_b128 v[202:205], v206 offset:2048
	ds_read_b128 v[206:209], v206 offset:3072
	global_load_lds_dwordx4 v[210:211], off
	v_lshl_add_u64 v[212:213], s[26:27], 0, v[194:195]
	s_add_i32 m0, s22, 0x2000
	s_nop 0
	global_load_lds_dwordx4 v[212:213], off
	s_barrier
	s_waitcnt lgkmcnt(0)
	s_setprio 1
	v_mfma_f32_16x16x32_bf16 v[118:121], v[178:181], v[146:149], v[118:121]
	v_mfma_f32_16x16x32_bf16 v[114:117], v[202:205], v[146:149], v[114:117]
	v_mfma_f32_16x16x32_bf16 v[102:105], v[178:181], v[154:157], v[102:105]
	v_mfma_f32_16x16x32_bf16 v[98:101], v[202:205], v[154:157], v[98:101]
	v_mfma_f32_16x16x32_bf16 v[86:89], v[178:181], v[162:165], v[86:89]
	v_mfma_f32_16x16x32_bf16 v[82:85], v[202:205], v[162:165], v[82:85]
	v_mfma_f32_16x16x32_bf16 v[70:73], v[178:181], v[170:173], v[70:73]
	v_mfma_f32_16x16x32_bf16 v[66:69], v[202:205], v[170:173], v[66:69]
	v_mfma_f32_16x16x32_bf16 v[118:121], v[182:185], v[150:153], v[118:121]
	v_mfma_f32_16x16x32_bf16 v[114:117], v[206:209], v[150:153], v[114:117]
	v_mfma_f32_16x16x32_bf16 v[102:105], v[182:185], v[158:161], v[102:105]
	v_mfma_f32_16x16x32_bf16 v[98:101], v[206:209], v[158:161], v[98:101]
	v_mfma_f32_16x16x32_bf16 v[86:89], v[182:185], v[166:169], v[86:89]
	v_mfma_f32_16x16x32_bf16 v[82:85], v[206:209], v[166:169], v[82:85]
	v_mfma_f32_16x16x32_bf16 v[70:73], v[182:185], v[174:177], v[70:73]
	v_mfma_f32_16x16x32_bf16 v[66:69], v[206:209], v[174:177], v[66:69]
	s_setprio 0
	s_mov_b32 m0, s34
	v_lshl_add_u64 v[220:221], s[28:29], 0, v[196:197]
	s_barrier
	ds_read_b128 v[146:149], v236 offset:16384
	ds_read_b128 v[150:153], v236 offset:17408
	ds_read_b128 v[154:157], v236 offset:18432
	ds_read_b128 v[158:161], v236 offset:19456
	ds_read_b128 v[162:165], v236 offset:20480
	ds_read_b128 v[166:169], v236 offset:21504
	ds_read_b128 v[170:173], v236 offset:22528
	ds_read_b128 v[174:177], v236 offset:23552
	global_load_lds_dwordx4 v[220:221], off
	v_lshl_add_u64 v[222:223], s[28:29], 0, v[194:195]
	s_mov_b32 m0, s35
	s_nop 0
	global_load_lds_dwordx4 v[222:223], off
	s_barrier
	s_waitcnt lgkmcnt(0)
	s_setprio 1
	v_mfma_f32_16x16x32_bf16 v[62:65], v[130:133], v[146:149], v[62:65]
	v_mfma_f32_16x16x32_bf16 v[58:61], v[138:141], v[146:149], v[58:61]
	v_mfma_f32_16x16x32_bf16 v[46:49], v[130:133], v[154:157], v[46:49]
	v_mfma_f32_16x16x32_bf16 v[42:45], v[138:141], v[154:157], v[42:45]
	v_mfma_f32_16x16x32_bf16 v[30:33], v[130:133], v[162:165], v[30:33]
	v_mfma_f32_16x16x32_bf16 v[26:29], v[138:141], v[162:165], v[26:29]
	v_mfma_f32_16x16x32_bf16 v[14:17], v[130:133], v[170:173], v[14:17]
	v_mfma_f32_16x16x32_bf16 v[10:13], v[138:141], v[170:173], v[10:13]
	v_mfma_f32_16x16x32_bf16 v[62:65], v[134:137], v[150:153], v[62:65]
	v_mfma_f32_16x16x32_bf16 v[58:61], v[142:145], v[150:153], v[58:61]
	v_mfma_f32_16x16x32_bf16 v[46:49], v[134:137], v[158:161], v[46:49]
	v_mfma_f32_16x16x32_bf16 v[42:45], v[142:145], v[158:161], v[42:45]
	v_mfma_f32_16x16x32_bf16 v[30:33], v[134:137], v[166:169], v[30:33]
	v_mfma_f32_16x16x32_bf16 v[26:29], v[142:145], v[166:169], v[26:29]
	v_mfma_f32_16x16x32_bf16 v[14:17], v[134:137], v[174:177], v[14:17]
	v_mfma_f32_16x16x32_bf16 v[10:13], v[142:145], v[174:177], v[10:13]
	s_setprio 0
	s_barrier
	s_add_u32 s22, s26, 0x160000
	s_addc_u32 s23, s27, 0
	s_add_i32 s48, s49, s5
	v_lshl_add_u64 v[130:131], s[22:23], 0, v[196:197]
	s_mov_b32 m0, s48
	s_nop 0
	global_load_lds_dwordx4 v[130:131], off
	v_lshl_add_u64 v[130:131], s[22:23], 0, v[194:195]
	s_add_i32 m0, s48, 0x2000
	s_nop 0
	global_load_lds_dwordx4 v[130:131], off
	s_waitcnt vmcnt(6)
	s_barrier
	s_setprio 1
	v_mfma_f32_16x16x32_bf16 v[54:57], v[178:181], v[146:149], v[54:57]
	v_mfma_f32_16x16x32_bf16 v[50:53], v[202:205], v[146:149], v[50:53]
	v_mfma_f32_16x16x32_bf16 v[38:41], v[178:181], v[154:157], v[38:41]
	v_mfma_f32_16x16x32_bf16 v[34:37], v[202:205], v[154:157], v[34:37]
	v_mfma_f32_16x16x32_bf16 v[22:25], v[178:181], v[162:165], v[22:25]
	v_mfma_f32_16x16x32_bf16 v[18:21], v[202:205], v[162:165], v[18:21]
	v_mfma_f32_16x16x32_bf16 v[6:9], v[178:181], v[170:173], v[6:9]
	v_mfma_f32_16x16x32_bf16 v[2:5], v[202:205], v[170:173], v[2:5]
	v_mfma_f32_16x16x32_bf16 v[54:57], v[182:185], v[150:153], v[54:57]
	v_mfma_f32_16x16x32_bf16 v[50:53], v[206:209], v[150:153], v[50:53]
	v_mfma_f32_16x16x32_bf16 v[38:41], v[182:185], v[158:161], v[38:41]
	v_mfma_f32_16x16x32_bf16 v[34:37], v[206:209], v[158:161], v[34:37]
	v_mfma_f32_16x16x32_bf16 v[22:25], v[182:185], v[166:169], v[22:25]
	v_mfma_f32_16x16x32_bf16 v[18:21], v[206:209], v[166:169], v[18:21]
	v_mfma_f32_16x16x32_bf16 v[6:9], v[182:185], v[174:177], v[6:9]
	v_mfma_f32_16x16x32_bf16 v[2:5], v[206:209], v[174:177], v[2:5]
	s_setprio 0
	s_add_i32 s48, 0, 0x18000
	v_add_u32_e32 v142, s48, v191
	s_barrier
	ds_read_b128 v[130:133], v142
	ds_read_b128 v[134:137], v142 offset:1024
	ds_read_b128 v[138:141], v142 offset:2048
	ds_read_b128 v[142:145], v142 offset:3072
	s_add_u32 s22, s28, 0x160000
	s_addc_u32 s23, s29, 0
	s_mov_b32 m0, s36
	v_lshl_add_u64 v[178:179], s[22:23], 0, v[196:197]
	ds_read_b128 v[146:149], v236 offset:32768
	ds_read_b128 v[150:153], v236 offset:33792
	ds_read_b128 v[154:157], v236 offset:34816
	ds_read_b128 v[158:161], v236 offset:35840
	ds_read_b128 v[162:165], v236 offset:36864
	ds_read_b128 v[166:169], v236 offset:37888
	ds_read_b128 v[170:173], v236 offset:38912
	ds_read_b128 v[174:177], v236 offset:39936
	global_load_lds_dwordx4 v[178:179], off
	v_lshl_add_u64 v[178:179], s[22:23], 0, v[194:195]
	s_mov_b32 m0, s37
	s_nop 0
	global_load_lds_dwordx4 v[178:179], off
	s_waitcnt lgkmcnt(8)
	s_barrier
	s_waitcnt lgkmcnt(0)
	s_setprio 1
	v_mfma_f32_16x16x32_bf16 v[126:129], v[130:133], v[146:149], v[126:129]
	v_mfma_f32_16x16x32_bf16 v[122:125], v[138:141], v[146:149], v[122:125]
	v_mfma_f32_16x16x32_bf16 v[110:113], v[130:133], v[154:157], v[110:113]
	v_mfma_f32_16x16x32_bf16 v[106:109], v[138:141], v[154:157], v[106:109]
	v_mfma_f32_16x16x32_bf16 v[94:97], v[130:133], v[162:165], v[94:97]
	v_mfma_f32_16x16x32_bf16 v[90:93], v[138:141], v[162:165], v[90:93]
	v_mfma_f32_16x16x32_bf16 v[78:81], v[130:133], v[170:173], v[78:81]
	v_mfma_f32_16x16x32_bf16 v[74:77], v[138:141], v[170:173], v[74:77]
	v_mfma_f32_16x16x32_bf16 v[126:129], v[134:137], v[150:153], v[126:129]
	v_mfma_f32_16x16x32_bf16 v[122:125], v[142:145], v[150:153], v[122:125]
	v_mfma_f32_16x16x32_bf16 v[110:113], v[134:137], v[158:161], v[110:113]
	v_mfma_f32_16x16x32_bf16 v[106:109], v[142:145], v[158:161], v[106:109]
	v_mfma_f32_16x16x32_bf16 v[94:97], v[134:137], v[166:169], v[94:97]
	v_mfma_f32_16x16x32_bf16 v[90:93], v[142:145], v[166:169], v[90:93]
	v_mfma_f32_16x16x32_bf16 v[78:81], v[134:137], v[174:177], v[78:81]
	v_mfma_f32_16x16x32_bf16 v[74:77], v[142:145], v[174:177], v[74:77]
	s_setprio 0
	s_barrier
	s_add_i32 s28, 0, 0x1c000
	s_add_i32 s22, s48, s5
	v_add_u32_e32 v206, s28, v191
	v_lshl_add_u64 v[210:211], v[210:211], 0, s[6:7]
	s_mov_b32 m0, s22
	ds_read_b128 v[178:181], v206
	ds_read_b128 v[182:185], v206 offset:1024
	ds_read_b128 v[202:205], v206 offset:2048
	ds_read_b128 v[206:209], v206 offset:3072
	global_load_lds_dwordx4 v[210:211], off
	v_lshl_add_u64 v[210:211], v[212:213], 0, s[6:7]
	s_add_i32 m0, s22, 0x2000
	s_nop 0
	global_load_lds_dwordx4 v[210:211], off
	s_barrier
	s_waitcnt lgkmcnt(0)
	s_setprio 1
	v_mfma_f32_16x16x32_bf16 v[118:121], v[178:181], v[146:149], v[118:121]
	v_mfma_f32_16x16x32_bf16 v[114:117], v[202:205], v[146:149], v[114:117]
	v_mfma_f32_16x16x32_bf16 v[102:105], v[178:181], v[154:157], v[102:105]
	v_mfma_f32_16x16x32_bf16 v[98:101], v[202:205], v[154:157], v[98:101]
	v_mfma_f32_16x16x32_bf16 v[86:89], v[178:181], v[162:165], v[86:89]
	v_mfma_f32_16x16x32_bf16 v[82:85], v[202:205], v[162:165], v[82:85]
	v_mfma_f32_16x16x32_bf16 v[70:73], v[178:181], v[170:173], v[70:73]
	v_mfma_f32_16x16x32_bf16 v[66:69], v[202:205], v[170:173], v[66:69]
	v_mfma_f32_16x16x32_bf16 v[118:121], v[182:185], v[150:153], v[118:121]
	v_mfma_f32_16x16x32_bf16 v[114:117], v[206:209], v[150:153], v[114:117]
	v_mfma_f32_16x16x32_bf16 v[102:105], v[182:185], v[158:161], v[102:105]
	v_mfma_f32_16x16x32_bf16 v[98:101], v[206:209], v[158:161], v[98:101]
	v_mfma_f32_16x16x32_bf16 v[86:89], v[182:185], v[166:169], v[86:89]
	v_mfma_f32_16x16x32_bf16 v[82:85], v[206:209], v[166:169], v[82:85]
	v_mfma_f32_16x16x32_bf16 v[70:73], v[182:185], v[174:177], v[70:73]
	v_mfma_f32_16x16x32_bf16 v[66:69], v[206:209], v[174:177], v[66:69]
	s_setprio 0
	s_mov_b32 m0, s38
	v_lshl_add_u64 v[210:211], v[220:221], 0, s[6:7]
	s_barrier
	ds_read_b128 v[146:149], v236 offset:49152
	ds_read_b128 v[150:153], v236 offset:50176
	ds_read_b128 v[154:157], v236 offset:51200
	ds_read_b128 v[158:161], v236 offset:52224
	ds_read_b128 v[162:165], v236 offset:53248
	ds_read_b128 v[166:169], v236 offset:54272
	ds_read_b128 v[170:173], v236 offset:55296
	ds_read_b128 v[174:177], v236 offset:56320
	global_load_lds_dwordx4 v[210:211], off
	v_lshl_add_u64 v[210:211], v[222:223], 0, s[6:7]
	s_mov_b32 m0, s39
	s_nop 0
	global_load_lds_dwordx4 v[210:211], off
	s_barrier
	s_waitcnt lgkmcnt(0)
	s_setprio 1
	v_mfma_f32_16x16x32_bf16 v[62:65], v[130:133], v[146:149], v[62:65]
	v_mfma_f32_16x16x32_bf16 v[58:61], v[138:141], v[146:149], v[58:61]
	v_mfma_f32_16x16x32_bf16 v[46:49], v[130:133], v[154:157], v[46:49]
	v_mfma_f32_16x16x32_bf16 v[42:45], v[138:141], v[154:157], v[42:45]
	v_mfma_f32_16x16x32_bf16 v[30:33], v[130:133], v[162:165], v[30:33]
	v_mfma_f32_16x16x32_bf16 v[26:29], v[138:141], v[162:165], v[26:29]
	v_mfma_f32_16x16x32_bf16 v[14:17], v[130:133], v[170:173], v[14:17]
	v_mfma_f32_16x16x32_bf16 v[10:13], v[138:141], v[170:173], v[10:13]
	v_mfma_f32_16x16x32_bf16 v[62:65], v[134:137], v[150:153], v[62:65]
	v_mfma_f32_16x16x32_bf16 v[58:61], v[142:145], v[150:153], v[58:61]
	v_mfma_f32_16x16x32_bf16 v[46:49], v[134:137], v[158:161], v[46:49]
	v_mfma_f32_16x16x32_bf16 v[42:45], v[142:145], v[158:161], v[42:45]
	v_mfma_f32_16x16x32_bf16 v[30:33], v[134:137], v[166:169], v[30:33]
	v_mfma_f32_16x16x32_bf16 v[26:29], v[142:145], v[166:169], v[26:29]
	v_mfma_f32_16x16x32_bf16 v[14:17], v[134:137], v[174:177], v[14:17]
	v_mfma_f32_16x16x32_bf16 v[10:13], v[142:145], v[174:177], v[10:13]
	s_setprio 0
	s_barrier
	s_add_u32 s22, s26, 0x160080
	s_addc_u32 s23, s27, 0
	s_add_i32 s26, s28, s5
	v_lshl_add_u64 v[130:131], s[22:23], 0, v[196:197]
	s_mov_b32 m0, s26
	s_nop 0
	global_load_lds_dwordx4 v[130:131], off
	v_lshl_add_u64 v[130:131], s[22:23], 0, v[194:195]
	s_add_i32 m0, s26, 0x2000
	s_nop 0
	global_load_lds_dwordx4 v[130:131], off
	s_waitcnt vmcnt(6)
	s_barrier
	s_setprio 1
	v_mfma_f32_16x16x32_bf16 v[54:57], v[178:181], v[146:149], v[54:57]
	v_mfma_f32_16x16x32_bf16 v[50:53], v[202:205], v[146:149], v[50:53]
	v_mfma_f32_16x16x32_bf16 v[38:41], v[178:181], v[154:157], v[38:41]
	v_mfma_f32_16x16x32_bf16 v[34:37], v[202:205], v[154:157], v[34:37]
	v_mfma_f32_16x16x32_bf16 v[22:25], v[178:181], v[162:165], v[22:25]
	v_mfma_f32_16x16x32_bf16 v[18:21], v[202:205], v[162:165], v[18:21]
	v_mfma_f32_16x16x32_bf16 v[6:9], v[178:181], v[170:173], v[6:9]
	v_mfma_f32_16x16x32_bf16 v[2:5], v[202:205], v[170:173], v[2:5]
	v_mfma_f32_16x16x32_bf16 v[54:57], v[182:185], v[150:153], v[54:57]
	v_mfma_f32_16x16x32_bf16 v[50:53], v[206:209], v[150:153], v[50:53]
	v_mfma_f32_16x16x32_bf16 v[38:41], v[182:185], v[158:161], v[38:41]
	v_mfma_f32_16x16x32_bf16 v[34:37], v[206:209], v[158:161], v[34:37]
	v_mfma_f32_16x16x32_bf16 v[22:25], v[182:185], v[166:169], v[22:25]
	v_mfma_f32_16x16x32_bf16 v[18:21], v[206:209], v[166:169], v[18:21]
	v_mfma_f32_16x16x32_bf16 v[6:9], v[182:185], v[174:177], v[6:9]
	v_mfma_f32_16x16x32_bf16 v[2:5], v[206:209], v[174:177], v[2:5]
	s_setprio 0
	s_add_i32 s47, s47, 2
	s_add_u32 s45, s45, 0x100
	s_addc_u32 s46, s46, 0
	s_cmpk_gt_u32 s47, 0x55
	s_mov_b64 s[22:23], s[24:25]
	s_barrier
	s_cbranch_scc0 .LBB0_695
	s_nop 0
	s_nop 0
	s_nop 0
	s_nop 0
	s_nop 0
	s_nop 0
	v_lshl_add_u32 v202, s43, 8, v1
	v_lshl_or_b32 v204, s44, 8, v192
	v_ashrrev_i32_e32 v205, 31, v204
	v_ashrrev_i32_e32 v203, 31, v202
	v_lshl_add_u64 v[206:207], v[204:205], 2, s[18:19]
	v_lshlrev_b64 v[130:131], 13, v[202:203]
	v_lshl_add_u64 v[130:131], v[206:207], 0, v[130:131]
	global_load_dwordx4 v[238:241], v[130:131], off
	global_load_dwordx4 v[242:245], v[130:131], off offset:64
	global_load_dwordx4 v[182:185], v[130:131], off offset:512
	global_load_dwordx4 v[178:181], v[130:131], off offset:576
	v_or_b32_e32 v212, 16, v202
	v_ashrrev_i32_e32 v213, 31, v212
	v_lshlrev_b64 v[130:131], 13, v[212:213]
	v_or_b32_e32 v210, 32, v202
	v_lshl_add_u64 v[130:131], v[206:207], 0, v[130:131]
	v_ashrrev_i32_e32 v211, 31, v210
	global_load_dwordx4 v[174:177], v[130:131], off
	global_load_dwordx4 v[170:173], v[130:131], off offset:64
	global_load_dwordx4 v[166:169], v[130:131], off offset:512
	global_load_dwordx4 v[162:165], v[130:131], off offset:576
	v_lshlrev_b64 v[130:131], 13, v[210:211]
	v_or_b32_e32 v208, 48, v202
	v_lshl_add_u64 v[130:131], v[206:207], 0, v[130:131]
	v_ashrrev_i32_e32 v209, 31, v208
	global_load_dwordx4 v[158:161], v[130:131], off
	global_load_dwordx4 v[150:153], v[130:131], off offset:64
	global_load_dwordx4 v[146:149], v[130:131], off offset:512
	global_load_dwordx4 v[138:141], v[130:131], off offset:576
	v_lshlrev_b64 v[130:131], 13, v[208:209]
	v_lshl_add_u64 v[130:131], v[206:207], 0, v[130:131]
	global_load_dwordx4 v[154:157], v[130:131], off
	global_load_dwordx4 v[142:145], v[130:131], off offset:64
	global_load_dwordx4 v[134:137], v[130:131], off offset:512
	s_nop 0
	global_load_dwordx4 v[130:133], v[130:131], off offset:576
	v_lshlrev_b64 v[220:221], 11, v[202:203]
	v_readlane_b32 s24, v254, 46
	v_readlane_b32 s22, v254, 1
	v_lshl_add_u64 v[220:221], v[220:221], 0, v[204:205]
	v_readlane_b32 s25, v254, 47
	v_readlane_b32 s23, v254, 2
	v_readlane_b32 s26, v254, 48
	v_lshl_add_u64 v[222:223], v[220:221], 2, s[24:25]
	v_lshl_add_u64 v[220:221], v[220:221], 1, s[22:23]
	v_readlane_b32 s27, v254, 49
	s_waitcnt vmcnt(0)
	v_pk_fma_f32 v[128:129], v[128:129], 0.5, v[240:241] op_sel_hi:[1,0,1]
	v_pk_fma_f32 v[126:127], v[126:127], 0.5, v[238:239] op_sel_hi:[1,0,1]
	v_cvt_pk_bf16_f32 v239, v128, v129
	v_cvt_pk_bf16_f32 v238, v126, v127
	v_mul_f32_e32 v224, v127, v127
	v_pk_fma_f32 v[124:125], v[124:125], 0.5, v[244:245] op_sel_hi:[1,0,1]
	v_pk_fma_f32 v[122:123], v[122:123], 0.5, v[242:243] op_sel_hi:[1,0,1]
	global_store_dwordx4 v[222:223], v[126:129], off
	global_store_dwordx2 v[220:221], v[238:239], off
	v_fmac_f32_e32 v224, v126, v126
	global_store_dwordx4 v[222:223], v[122:125], off offset:64
	v_cvt_pk_bf16_f32 v126, v122, v123
	v_fmac_f32_e32 v224, v128, v128
	v_mul_f32_e32 v123, v123, v123
	v_fmac_f32_e32 v123, v122, v122
	v_fmac_f32_e32 v123, v124, v124
	v_fmac_f32_e32 v224, v129, v129
	v_cvt_pk_bf16_f32 v127, v124, v125
	v_fmac_f32_e32 v123, v125, v125
	v_pk_fma_f32 v[120:121], v[120:121], 0.5, v[184:185] op_sel_hi:[1,0,1]
	v_pk_fma_f32 v[118:119], v[118:119], 0.5, v[182:183] op_sel_hi:[1,0,1]
	global_store_dwordx2 v[220:221], v[126:127], off offset:32
	v_add_f32_e32 v124, v224, v123
	global_store_dwordx4 v[222:223], v[118:121], off offset:512
	v_cvt_pk_bf16_f32 v122, v118, v119
	v_cvt_pk_bf16_f32 v123, v120, v121
	v_mul_f32_e32 v119, v119, v119
	v_pk_fma_f32 v[116:117], v[116:117], 0.5, v[180:181] op_sel_hi:[1,0,1]
	v_pk_fma_f32 v[114:115], v[114:115], 0.5, v[178:179] op_sel_hi:[1,0,1]
	global_store_dwordx2 v[220:221], v[122:123], off offset:256
	v_fmac_f32_e32 v119, v118, v118
	global_store_dwordx4 v[222:223], v[114:117], off offset:576
	v_cvt_pk_bf16_f32 v118, v114, v115
	v_fmac_f32_e32 v119, v120, v120
	v_mul_f32_e32 v115, v115, v115
	v_fmac_f32_e32 v115, v114, v114
	v_fmac_f32_e32 v119, v121, v121
	v_fmac_f32_e32 v115, v116, v116
	v_add_f32_e32 v120, v124, v119
	v_fmac_f32_e32 v115, v117, v117
	v_add_f32_e32 v114, v120, v115
	v_mov_b32_e32 v115, v114
	s_nop 1
	v_permlane32_swap_b32_e32 v114, v115
	v_add_f32_e32 v114, v114, v115
	v_mov_b32_e32 v115, v114
	v_cvt_pk_bf16_f32 v119, v116, v117
	s_nop 0
	v_permlane16_swap_b32_e32 v114, v115
	global_store_dwordx2 v[220:221], v[118:119], off offset:288
	s_and_saveexec_b64 s[22:23], s[10:11]
	s_cbranch_execz .LBB0_698
	v_lshl_add_u64 v[116:117], v[202:203], 2, s[20:21]
	v_add_f32_e32 v114, v114, v115
	global_atomic_add_f32 v[116:117], v114, off

.LBB0_732:
	s_add_u32 s18, s16, 0x100
	s_addc_u32 s19, s17, 0
	s_add_i32 s40, 0, 0x10000
	v_add_u32_e32 v153, s40, v150
	ds_read_b128 v[138:141], v153
	ds_read_b128 v[142:145], v153 offset:1024
	ds_read_b128 v[146:149], v153 offset:2048
	ds_read_b128 v[154:157], v153 offset:3072
	s_cmpk_eq_i32 s39, 0x54
	s_cselect_b32 s23, s13, s19
	s_cselect_b32 s22, s12, s18
	s_cselect_b32 s21, s15, s38
	s_cselect_b32 s20, s14, s37
	v_lshl_add_u64 v[198:199], s[16:17], 0, v[134:135]
	s_add_i32 m0, s24, 0xc000
	ds_read_b128 v[158:161], v152
	ds_read_b128 v[162:165], v152 offset:1024
	ds_read_b128 v[166:169], v152 offset:2048
	ds_read_b128 v[170:173], v152 offset:3072
	ds_read_b128 v[174:177], v152 offset:4096
	ds_read_b128 v[178:181], v152 offset:5120
	ds_read_b128 v[182:185], v152 offset:6144
	ds_read_b128 v[194:197], v152 offset:7168
	global_load_lds_dwordx4 v[198:199], off
	v_lshl_add_u64 v[198:199], s[16:17], 0, v[136:137]
	s_add_i32 m0, s24, 0xe000
	s_nop 0
	global_load_lds_dwordx4 v[198:199], off
	s_waitcnt lgkmcnt(8)
	s_barrier
	s_waitcnt lgkmcnt(0)
	s_setprio 1
	v_mfma_f32_16x16x32_bf16 v[126:129], v[138:141], v[158:161], v[126:129]
	v_mfma_f32_16x16x32_bf16 v[122:125], v[146:149], v[158:161], v[122:125]
	v_mfma_f32_16x16x32_bf16 v[118:121], v[138:141], v[166:169], v[118:121]
	v_mfma_f32_16x16x32_bf16 v[114:117], v[146:149], v[166:169], v[114:117]
	v_mfma_f32_16x16x32_bf16 v[106:109], v[138:141], v[174:177], v[106:109]
	v_mfma_f32_16x16x32_bf16 v[98:101], v[146:149], v[174:177], v[98:101]
	v_mfma_f32_16x16x32_bf16 v[90:93], v[138:141], v[182:185], v[90:93]
	v_mfma_f32_16x16x32_bf16 v[82:85], v[146:149], v[182:185], v[82:85]
	v_mfma_f32_16x16x32_bf16 v[126:129], v[142:145], v[162:165], v[126:129]
	v_mfma_f32_16x16x32_bf16 v[122:125], v[154:157], v[162:165], v[122:125]
	v_mfma_f32_16x16x32_bf16 v[118:121], v[142:145], v[170:173], v[118:121]
	v_mfma_f32_16x16x32_bf16 v[114:117], v[154:157], v[170:173], v[114:117]
	v_mfma_f32_16x16x32_bf16 v[106:109], v[142:145], v[178:181], v[106:109]
	v_mfma_f32_16x16x32_bf16 v[98:101], v[154:157], v[178:181], v[98:101]
	v_mfma_f32_16x16x32_bf16 v[90:93], v[142:145], v[194:197], v[90:93]
	v_mfma_f32_16x16x32_bf16 v[82:85], v[154:157], v[194:197], v[82:85]
	s_setprio 0
	s_barrier
	s_add_i32 s41, 0, 0x14000
	s_add_i32 s16, s40, s5
	v_add_u32_e32 v153, s41, v150
	v_lshl_add_u64 v[220:221], s[20:21], 0, v[132:133]
	s_mov_b32 m0, s16
	ds_read_b128 v[198:201], v153
	ds_read_b128 v[202:205], v153 offset:1024
	ds_read_b128 v[206:209], v153 offset:2048
	ds_read_b128 v[210:213], v153 offset:3072
	global_load_lds_dwordx4 v[220:221], off
	v_lshl_add_u64 v[222:223], s[20:21], 0, v[130:131]
	s_add_i32 m0, s16, 0x2000
	s_nop 0
	global_load_lds_dwordx4 v[222:223], off
	s_barrier
	s_waitcnt lgkmcnt(0)
	s_setprio 1
	v_mfma_f32_16x16x32_bf16 v[110:113], v[198:201], v[158:161], v[110:113]
	v_mfma_f32_16x16x32_bf16 v[102:105], v[206:209], v[158:161], v[102:105]
	v_mfma_f32_16x16x32_bf16 v[94:97], v[198:201], v[166:169], v[94:97]
	v_mfma_f32_16x16x32_bf16 v[86:89], v[206:209], v[166:169], v[86:89]
	v_mfma_f32_16x16x32_bf16 v[78:81], v[198:201], v[174:177], v[78:81]
	v_mfma_f32_16x16x32_bf16 v[74:77], v[206:209], v[174:177], v[74:77]
	v_mfma_f32_16x16x32_bf16 v[70:73], v[198:201], v[182:185], v[70:73]
	v_mfma_f32_16x16x32_bf16 v[66:69], v[206:209], v[182:185], v[66:69]
	v_mfma_f32_16x16x32_bf16 v[110:113], v[202:205], v[162:165], v[110:113]
	v_mfma_f32_16x16x32_bf16 v[102:105], v[210:213], v[162:165], v[102:105]
	v_mfma_f32_16x16x32_bf16 v[94:97], v[202:205], v[170:173], v[94:97]
	v_mfma_f32_16x16x32_bf16 v[86:89], v[210:213], v[170:173], v[86:89]
	v_mfma_f32_16x16x32_bf16 v[78:81], v[202:205], v[178:181], v[78:81]
	v_mfma_f32_16x16x32_bf16 v[74:77], v[210:213], v[178:181], v[74:77]
	v_mfma_f32_16x16x32_bf16 v[70:73], v[202:205], v[194:197], v[70:73]
	v_mfma_f32_16x16x32_bf16 v[66:69], v[210:213], v[194:197], v[66:69]
	s_setprio 0
	s_mov_b32 m0, s24
	v_lshl_add_u64 v[236:237], s[22:23], 0, v[132:133]
	s_barrier
	ds_read_b128 v[158:161], v152 offset:16384
	ds_read_b128 v[162:165], v152 offset:17408
	ds_read_b128 v[166:169], v152 offset:18432
	ds_read_b128 v[170:173], v152 offset:19456
	ds_read_b128 v[174:177], v152 offset:20480
	ds_read_b128 v[178:181], v152 offset:21504
	ds_read_b128 v[182:185], v152 offset:22528
	ds_read_b128 v[194:197], v152 offset:23552
	global_load_lds_dwordx4 v[236:237], off
	v_lshl_add_u64 v[238:239], s[22:23], 0, v[130:131]
	s_mov_b32 m0, s25
	s_nop 0
	global_load_lds_dwordx4 v[238:239], off
	s_barrier
	s_waitcnt lgkmcnt(0)
	s_setprio 1
	v_mfma_f32_16x16x32_bf16 v[62:65], v[138:141], v[158:161], v[62:65]
	v_mfma_f32_16x16x32_bf16 v[58:61], v[146:149], v[158:161], v[58:61]
	v_mfma_f32_16x16x32_bf16 v[54:57], v[138:141], v[166:169], v[54:57]
	v_mfma_f32_16x16x32_bf16 v[46:49], v[146:149], v[166:169], v[46:49]
	v_mfma_f32_16x16x32_bf16 v[38:41], v[138:141], v[174:177], v[38:41]
	v_mfma_f32_16x16x32_bf16 v[30:33], v[146:149], v[174:177], v[30:33]
	v_mfma_f32_16x16x32_bf16 v[22:25], v[138:141], v[182:185], v[22:25]
	v_mfma_f32_16x16x32_bf16 v[10:13], v[146:149], v[182:185], v[10:13]
	v_mfma_f32_16x16x32_bf16 v[62:65], v[142:145], v[162:165], v[62:65]
	v_mfma_f32_16x16x32_bf16 v[58:61], v[154:157], v[162:165], v[58:61]
	v_mfma_f32_16x16x32_bf16 v[54:57], v[142:145], v[170:173], v[54:57]
	v_mfma_f32_16x16x32_bf16 v[46:49], v[154:157], v[170:173], v[46:49]
	v_mfma_f32_16x16x32_bf16 v[38:41], v[142:145], v[178:181], v[38:41]
	v_mfma_f32_16x16x32_bf16 v[30:33], v[154:157], v[178:181], v[30:33]
	v_mfma_f32_16x16x32_bf16 v[22:25], v[142:145], v[194:197], v[22:25]
	v_mfma_f32_16x16x32_bf16 v[10:13], v[154:157], v[194:197], v[10:13]
	s_setprio 0
	s_barrier
	s_add_u32 s16, s20, 0x160000
	s_addc_u32 s17, s21, 0
	s_add_i32 s40, s41, s5
	v_lshl_add_u64 v[138:139], s[16:17], 0, v[132:133]
	s_mov_b32 m0, s40
	s_nop 0
	global_load_lds_dwordx4 v[138:139], off
	v_lshl_add_u64 v[138:139], s[16:17], 0, v[130:131]
	s_add_i32 m0, s40, 0x2000
	s_nop 0
	global_load_lds_dwordx4 v[138:139], off
	s_waitcnt vmcnt(6)
	s_barrier
	s_setprio 1
	v_mfma_f32_16x16x32_bf16 v[50:53], v[198:201], v[158:161], v[50:53]
	v_mfma_f32_16x16x32_bf16 v[42:45], v[206:209], v[158:161], v[42:45]
	v_mfma_f32_16x16x32_bf16 v[34:37], v[198:201], v[166:169], v[34:37]
	v_mfma_f32_16x16x32_bf16 v[26:29], v[206:209], v[166:169], v[26:29]
	v_mfma_f32_16x16x32_bf16 v[18:21], v[198:201], v[174:177], v[18:21]
	v_mfma_f32_16x16x32_bf16 v[14:17], v[206:209], v[174:177], v[14:17]
	v_mfma_f32_16x16x32_bf16 v[6:9], v[198:201], v[182:185], v[6:9]
	v_mfma_f32_16x16x32_bf16 v[2:5], v[206:209], v[182:185], v[2:5]
	v_mfma_f32_16x16x32_bf16 v[50:53], v[202:205], v[162:165], v[50:53]
	v_mfma_f32_16x16x32_bf16 v[42:45], v[210:213], v[162:165], v[42:45]
	v_mfma_f32_16x16x32_bf16 v[34:37], v[202:205], v[170:173], v[34:37]
	v_mfma_f32_16x16x32_bf16 v[26:29], v[210:213], v[170:173], v[26:29]
	v_mfma_f32_16x16x32_bf16 v[18:21], v[202:205], v[178:181], v[18:21]
	v_mfma_f32_16x16x32_bf16 v[14:17], v[210:213], v[178:181], v[14:17]
	v_mfma_f32_16x16x32_bf16 v[6:9], v[202:205], v[194:197], v[6:9]
	v_mfma_f32_16x16x32_bf16 v[2:5], v[210:213], v[194:197], v[2:5]
	s_setprio 0
	s_add_i32 s40, 0, 0x18000
	v_add_u32_e32 v153, s40, v150
	s_barrier
	ds_read_b128 v[138:141], v153
	ds_read_b128 v[142:145], v153 offset:1024
	ds_read_b128 v[146:149], v153 offset:2048
	ds_read_b128 v[154:157], v153 offset:3072
	s_add_u32 s16, s22, 0x160000
	s_addc_u32 s17, s23, 0
	s_mov_b32 m0, s26
	v_lshl_add_u64 v[198:199], s[16:17], 0, v[132:133]
	ds_read_b128 v[158:161], v152 offset:32768
	ds_read_b128 v[162:165], v152 offset:33792
	ds_read_b128 v[166:169], v152 offset:34816
	ds_read_b128 v[170:173], v152 offset:35840
	ds_read_b128 v[174:177], v152 offset:36864
	ds_read_b128 v[178:181], v152 offset:37888
	ds_read_b128 v[182:185], v152 offset:38912
	ds_read_b128 v[194:197], v152 offset:39936
	global_load_lds_dwordx4 v[198:199], off
	v_lshl_add_u64 v[198:199], s[16:17], 0, v[130:131]
	s_mov_b32 m0, s27
	s_nop 0
	global_load_lds_dwordx4 v[198:199], off
	s_waitcnt lgkmcnt(8)
	s_barrier
	s_waitcnt lgkmcnt(0)
	s_setprio 1
	v_mfma_f32_16x16x32_bf16 v[126:129], v[138:141], v[158:161], v[126:129]
	v_mfma_f32_16x16x32_bf16 v[122:125], v[146:149], v[158:161], v[122:125]
	v_mfma_f32_16x16x32_bf16 v[118:121], v[138:141], v[166:169], v[118:121]
	v_mfma_f32_16x16x32_bf16 v[114:117], v[146:149], v[166:169], v[114:117]
	v_mfma_f32_16x16x32_bf16 v[106:109], v[138:141], v[174:177], v[106:109]
	v_mfma_f32_16x16x32_bf16 v[98:101], v[146:149], v[174:177], v[98:101]
	v_mfma_f32_16x16x32_bf16 v[90:93], v[138:141], v[182:185], v[90:93]
	v_mfma_f32_16x16x32_bf16 v[82:85], v[146:149], v[182:185], v[82:85]
	v_mfma_f32_16x16x32_bf16 v[126:129], v[142:145], v[162:165], v[126:129]
	v_mfma_f32_16x16x32_bf16 v[122:125], v[154:157], v[162:165], v[122:125]
	v_mfma_f32_16x16x32_bf16 v[118:121], v[142:145], v[170:173], v[118:121]
	v_mfma_f32_16x16x32_bf16 v[114:117], v[154:157], v[170:173], v[114:117]
	v_mfma_f32_16x16x32_bf16 v[106:109], v[142:145], v[178:181], v[106:109]
	v_mfma_f32_16x16x32_bf16 v[98:101], v[154:157], v[178:181], v[98:101]
	v_mfma_f32_16x16x32_bf16 v[90:93], v[142:145], v[194:197], v[90:93]
	v_mfma_f32_16x16x32_bf16 v[82:85], v[154:157], v[194:197], v[82:85]
	s_setprio 0
	s_barrier
	s_add_i32 s22, 0, 0x1c000
	s_add_i32 s16, s40, s5
	v_add_u32_e32 v153, s22, v150
	v_lshl_add_u64 v[220:221], v[220:221], 0, s[6:7]
	s_mov_b32 m0, s16
	ds_read_b128 v[198:201], v153
	ds_read_b128 v[202:205], v153 offset:1024
	ds_read_b128 v[206:209], v153 offset:2048
	ds_read_b128 v[210:213], v153 offset:3072
	global_load_lds_dwordx4 v[220:221], off
	v_lshl_add_u64 v[220:221], v[222:223], 0, s[6:7]
	s_add_i32 m0, s16, 0x2000
	s_nop 0
	global_load_lds_dwordx4 v[220:221], off
	s_barrier
	s_waitcnt lgkmcnt(0)
	s_setprio 1
	v_mfma_f32_16x16x32_bf16 v[110:113], v[198:201], v[158:161], v[110:113]
	v_mfma_f32_16x16x32_bf16 v[102:105], v[206:209], v[158:161], v[102:105]
	v_mfma_f32_16x16x32_bf16 v[94:97], v[198:201], v[166:169], v[94:97]
	v_mfma_f32_16x16x32_bf16 v[86:89], v[206:209], v[166:169], v[86:89]
	v_mfma_f32_16x16x32_bf16 v[78:81], v[198:201], v[174:177], v[78:81]
	v_mfma_f32_16x16x32_bf16 v[74:77], v[206:209], v[174:177], v[74:77]
	v_mfma_f32_16x16x32_bf16 v[70:73], v[198:201], v[182:185], v[70:73]
	v_mfma_f32_16x16x32_bf16 v[66:69], v[206:209], v[182:185], v[66:69]
	v_mfma_f32_16x16x32_bf16 v[110:113], v[202:205], v[162:165], v[110:113]
	v_mfma_f32_16x16x32_bf16 v[102:105], v[210:213], v[162:165], v[102:105]
	v_mfma_f32_16x16x32_bf16 v[94:97], v[202:205], v[170:173], v[94:97]
	v_mfma_f32_16x16x32_bf16 v[86:89], v[210:213], v[170:173], v[86:89]
	v_mfma_f32_16x16x32_bf16 v[78:81], v[202:205], v[178:181], v[78:81]
	v_mfma_f32_16x16x32_bf16 v[74:77], v[210:213], v[178:181], v[74:77]
	v_mfma_f32_16x16x32_bf16 v[70:73], v[202:205], v[194:197], v[70:73]
	v_mfma_f32_16x16x32_bf16 v[66:69], v[210:213], v[194:197], v[66:69]
	s_setprio 0
	s_mov_b32 m0, s28
	v_lshl_add_u64 v[220:221], v[236:237], 0, s[6:7]
	s_barrier
	ds_read_b128 v[158:161], v152 offset:49152
	ds_read_b128 v[162:165], v152 offset:50176
	ds_read_b128 v[166:169], v152 offset:51200
	ds_read_b128 v[170:173], v152 offset:52224
	ds_read_b128 v[174:177], v152 offset:53248
	ds_read_b128 v[178:181], v152 offset:54272
	ds_read_b128 v[182:185], v152 offset:55296
	ds_read_b128 v[194:197], v152 offset:56320
	global_load_lds_dwordx4 v[220:221], off
	v_lshl_add_u64 v[220:221], v[238:239], 0, s[6:7]
	s_mov_b32 m0, s29
	s_nop 0
	global_load_lds_dwordx4 v[220:221], off
	s_barrier
	s_waitcnt lgkmcnt(0)
	s_setprio 1
	v_mfma_f32_16x16x32_bf16 v[62:65], v[138:141], v[158:161], v[62:65]
	v_mfma_f32_16x16x32_bf16 v[58:61], v[146:149], v[158:161], v[58:61]
	v_mfma_f32_16x16x32_bf16 v[54:57], v[138:141], v[166:169], v[54:57]
	v_mfma_f32_16x16x32_bf16 v[46:49], v[146:149], v[166:169], v[46:49]
	v_mfma_f32_16x16x32_bf16 v[38:41], v[138:141], v[174:177], v[38:41]
	v_mfma_f32_16x16x32_bf16 v[30:33], v[146:149], v[174:177], v[30:33]
	v_mfma_f32_16x16x32_bf16 v[22:25], v[138:141], v[182:185], v[22:25]
	v_mfma_f32_16x16x32_bf16 v[10:13], v[146:149], v[182:185], v[10:13]
	v_mfma_f32_16x16x32_bf16 v[62:65], v[142:145], v[162:165], v[62:65]
	v_mfma_f32_16x16x32_bf16 v[58:61], v[154:157], v[162:165], v[58:61]
	v_mfma_f32_16x16x32_bf16 v[54:57], v[142:145], v[170:173], v[54:57]
	v_mfma_f32_16x16x32_bf16 v[46:49], v[154:157], v[170:173], v[46:49]
	v_mfma_f32_16x16x32_bf16 v[38:41], v[142:145], v[178:181], v[38:41]
	v_mfma_f32_16x16x32_bf16 v[30:33], v[154:157], v[178:181], v[30:33]
	v_mfma_f32_16x16x32_bf16 v[22:25], v[142:145], v[194:197], v[22:25]
	v_mfma_f32_16x16x32_bf16 v[10:13], v[154:157], v[194:197], v[10:13]
	s_setprio 0
	s_barrier
	s_add_u32 s16, s20, 0x160080
	s_addc_u32 s17, s21, 0
	s_add_i32 s20, s22, s5
	v_lshl_add_u64 v[138:139], s[16:17], 0, v[132:133]
	s_mov_b32 m0, s20
	s_nop 0
	global_load_lds_dwordx4 v[138:139], off
	v_lshl_add_u64 v[138:139], s[16:17], 0, v[130:131]
	s_add_i32 m0, s20, 0x2000
	s_nop 0
	global_load_lds_dwordx4 v[138:139], off
	s_waitcnt vmcnt(6)
	s_barrier
	s_setprio 1
	v_mfma_f32_16x16x32_bf16 v[50:53], v[198:201], v[158:161], v[50:53]
	v_mfma_f32_16x16x32_bf16 v[42:45], v[206:209], v[158:161], v[42:45]
	v_mfma_f32_16x16x32_bf16 v[34:37], v[198:201], v[166:169], v[34:37]
	v_mfma_f32_16x16x32_bf16 v[26:29], v[206:209], v[166:169], v[26:29]
	v_mfma_f32_16x16x32_bf16 v[18:21], v[198:201], v[174:177], v[18:21]
	v_mfma_f32_16x16x32_bf16 v[14:17], v[206:209], v[174:177], v[14:17]
	v_mfma_f32_16x16x32_bf16 v[6:9], v[198:201], v[182:185], v[6:9]
	v_mfma_f32_16x16x32_bf16 v[2:5], v[206:209], v[182:185], v[2:5]
	v_mfma_f32_16x16x32_bf16 v[50:53], v[202:205], v[162:165], v[50:53]
	v_mfma_f32_16x16x32_bf16 v[42:45], v[210:213], v[162:165], v[42:45]
	v_mfma_f32_16x16x32_bf16 v[34:37], v[202:205], v[170:173], v[34:37]
	v_mfma_f32_16x16x32_bf16 v[26:29], v[210:213], v[170:173], v[26:29]
	v_mfma_f32_16x16x32_bf16 v[18:21], v[202:205], v[178:181], v[18:21]
	v_mfma_f32_16x16x32_bf16 v[14:17], v[210:213], v[178:181], v[14:17]
	v_mfma_f32_16x16x32_bf16 v[6:9], v[202:205], v[194:197], v[6:9]
	v_mfma_f32_16x16x32_bf16 v[2:5], v[210:213], v[194:197], v[2:5]
	s_setprio 0
	s_add_i32 s39, s39, 2
	s_add_u32 s37, s37, 0x100
	s_addc_u32 s38, s38, 0
	s_cmpk_gt_u32 s39, 0x55
	s_mov_b64 s[16:17], s[18:19]
	s_barrier
	s_cbranch_scc0 .LBB0_732
	s_nop 0
	s_nop 0
	s_nop 0
	s_nop 0
	s_nop 0
	s_nop 0
	v_lshl_or_b32 v138, s36, 8, v151
	v_lshl_add_u32 v140, s35, 8, v1
	v_ashrrev_i32_e32 v139, 31, v138
	v_readlane_b32 s20, v254, 46
	v_lshlrev_b64 v[138:139], 2, v[138:139]
	v_readlane_b32 s21, v254, 47
	v_ashrrev_i32_e32 v141, 31, v140
	v_lshlrev_b64 v[144:145], 13, v[140:141]
	v_lshl_add_u64 v[142:143], s[20:21], 0, v[138:139]
	v_or_b32_e32 v166, 16, v140
	v_lshl_add_u64 v[162:163], v[142:143], 0, v[144:145]
	v_ashrrev_i32_e32 v167, 31, v166
	global_load_dwordx4 v[146:149], v[162:163], off
	global_load_dwordx4 v[154:157], v[162:163], off offset:64
	global_load_dwordx4 v[158:161], v[162:163], off offset:512
	s_nop 0
	global_load_dwordx4 v[162:165], v[162:163], off offset:576
	v_lshlrev_b64 v[220:221], 13, v[166:167]
	v_or_b32_e32 v182, 32, v140
	v_lshl_add_u64 v[178:179], v[142:143], 0, v[220:221]
	v_ashrrev_i32_e32 v183, 31, v182
	global_load_dwordx4 v[166:169], v[178:179], off
	global_load_dwordx4 v[170:173], v[178:179], off offset:64
	global_load_dwordx4 v[174:177], v[178:179], off offset:512
	s_nop 0
	global_load_dwordx4 v[178:181], v[178:179], off offset:576
	v_lshlrev_b64 v[222:223], 13, v[182:183]
	v_or_b32_e32 v140, 48, v140
	v_lshl_add_u64 v[202:203], v[142:143], 0, v[222:223]
	v_ashrrev_i32_e32 v141, 31, v140
	global_load_dwordx4 v[182:185], v[202:203], off
	global_load_dwordx4 v[194:197], v[202:203], off offset:64
	global_load_dwordx4 v[198:201], v[202:203], off offset:512
	s_nop 0
	global_load_dwordx4 v[202:205], v[202:203], off offset:576
	v_lshlrev_b64 v[140:141], 13, v[140:141]
	v_lshl_add_u64 v[240:241], v[142:143], 0, v[140:141]
	global_load_dwordx4 v[206:209], v[240:241], off
	global_load_dwordx4 v[210:213], v[240:241], off offset:64
	global_load_dwordx4 v[236:239], v[240:241], off offset:512
	s_nop 0
	global_load_dwordx4 v[240:243], v[240:241], off offset:576
	s_mov_b64 s[16:17], 0x100000
	s_and_b64 vcc, exec, s[10:11]
	s_mov_b32 s35, s34
	s_mov_b32 s36, s31
	s_mov_b64 s[18:19], s[14:15]
	v_readlane_b32 s22, v254, 48
	v_readlane_b32 s23, v254, 49
	s_waitcnt vmcnt(0)
	v_pk_fma_f32 v[126:127], v[126:127], 0.5, v[146:147] op_sel_hi:[1,0,1]
	v_lshl_add_u64 v[146:147], s[20:21], 0, v[144:145]
	v_lshl_add_u64 v[146:147], v[146:147], 0, v[138:139]
	v_pk_fma_f32 v[112:113], v[112:113], 0.5, v[160:161] op_sel_hi:[1,0,1]
	v_pk_fma_f32 v[110:111], v[110:111], 0.5, v[158:159] op_sel_hi:[1,0,1]
	global_store_dwordx4 v[146:147], v[110:113], off offset:512
	v_pk_fma_f32 v[104:105], v[104:105], 0.5, v[164:165] op_sel_hi:[1,0,1]
	v_pk_fma_f32 v[96:97], v[96:97], 0.5, v[176:177] op_sel_hi:[1,0,1]
	v_lshl_add_u64 v[110:111], s[20:21], 0, v[220:221]
	v_lshl_add_u64 v[110:111], v[110:111], 0, v[138:139]
	v_pk_fma_f32 v[94:95], v[94:95], 0.5, v[174:175] op_sel_hi:[1,0,1]
	global_store_dwordx4 v[110:111], v[94:97], off offset:512
	v_pk_fma_f32 v[80:81], v[80:81], 0.5, v[200:201] op_sel_hi:[1,0,1]
	v_pk_fma_f32 v[78:79], v[78:79], 0.5, v[198:199] op_sel_hi:[1,0,1]
	v_lshl_add_u64 v[94:95], s[20:21], 0, v[222:223]
	v_lshl_add_u64 v[94:95], v[94:95], 0, v[138:139]
	v_pk_fma_f32 v[102:103], v[102:103], 0.5, v[162:163] op_sel_hi:[1,0,1]
	v_pk_fma_f32 v[88:89], v[88:89], 0.5, v[180:181] op_sel_hi:[1,0,1]
	v_pk_fma_f32 v[86:87], v[86:87], 0.5, v[178:179] op_sel_hi:[1,0,1]
	global_store_dwordx4 v[94:95], v[78:81], off offset:512
	v_pk_fma_f32 v[76:77], v[76:77], 0.5, v[204:205] op_sel_hi:[1,0,1]
	v_pk_fma_f32 v[74:75], v[74:75], 0.5, v[202:203] op_sel_hi:[1,0,1]
	v_lshl_add_u64 v[78:79], s[20:21], 0, v[140:141]
	global_store_dwordx4 v[146:147], v[102:105], off offset:576
	global_store_dwordx4 v[110:111], v[86:89], off offset:576
	global_store_dwordx4 v[94:95], v[74:77], off offset:576
	v_pk_fma_f32 v[104:105], v[120:121], 0.5, v[168:169] op_sel_hi:[1,0,1]
	v_pk_fma_f32 v[102:103], v[118:119], 0.5, v[166:167] op_sel_hi:[1,0,1]
	v_pk_fma_f32 v[88:89], v[108:109], 0.5, v[184:185] op_sel_hi:[1,0,1]
	v_pk_fma_f32 v[86:87], v[106:107], 0.5, v[182:183] op_sel_hi:[1,0,1]
	v_pk_fma_f32 v[76:77], v[92:93], 0.5, v[208:209] op_sel_hi:[1,0,1]
	v_pk_fma_f32 v[74:75], v[90:91], 0.5, v[206:207] op_sel_hi:[1,0,1]
	v_lshl_add_u64 v[78:79], v[78:79], 0, v[138:139]
	v_pk_fma_f32 v[128:129], v[128:129], 0.5, v[148:149] op_sel_hi:[1,0,1]
	v_pk_fma_f32 v[124:125], v[124:125], 0.5, v[156:157] op_sel_hi:[1,0,1]
	v_pk_fma_f32 v[122:123], v[122:123], 0.5, v[154:155] op_sel_hi:[1,0,1]
	global_store_dwordx4 v[110:111], v[102:105], off
	global_store_dwordx4 v[94:95], v[86:89], off
	global_store_dwordx4 v[78:79], v[74:77], off
	v_pk_fma_f32 v[104:105], v[116:117], 0.5, v[172:173] op_sel_hi:[1,0,1]
	v_pk_fma_f32 v[102:103], v[114:115], 0.5, v[170:171] op_sel_hi:[1,0,1]
	v_pk_fma_f32 v[88:89], v[100:101], 0.5, v[196:197] op_sel_hi:[1,0,1]
	v_pk_fma_f32 v[86:87], v[98:99], 0.5, v[194:195] op_sel_hi:[1,0,1]
	v_pk_fma_f32 v[76:77], v[84:85], 0.5, v[212:213] op_sel_hi:[1,0,1]
	v_pk_fma_f32 v[74:75], v[82:83], 0.5, v[210:211] op_sel_hi:[1,0,1]
	v_pk_fma_f32 v[72:73], v[72:73], 0.5, v[238:239] op_sel_hi:[1,0,1]
	v_pk_fma_f32 v[70:71], v[70:71], 0.5, v[236:237] op_sel_hi:[1,0,1]
	v_pk_fma_f32 v[68:69], v[68:69], 0.5, v[242:243] op_sel_hi:[1,0,1]
	v_pk_fma_f32 v[66:67], v[66:67], 0.5, v[240:241] op_sel_hi:[1,0,1]
	v_lshl_add_u64 v[140:141], v[144:145], 0, s[16:17]
	global_store_dwordx4 v[146:147], v[126:129], off
	global_store_dwordx4 v[146:147], v[122:125], off offset:64
	global_store_dwordx4 v[110:111], v[102:105], off offset:64
	global_store_dwordx4 v[94:95], v[86:89], off offset:64
	global_store_dwordx4 v[78:79], v[74:77], off offset:64
	global_store_dwordx4 v[78:79], v[70:73], off offset:512
	global_store_dwordx4 v[78:79], v[66:69], off offset:576
	s_mov_b64 s[16:17], 0x120000
	v_lshl_add_u64 v[148:149], v[144:145], 0, s[16:17]
	v_lshl_add_u64 v[66:67], v[142:143], 0, v[140:141]
	global_load_dwordx4 v[78:81], v[66:67], off
	global_load_dwordx4 v[74:77], v[66:67], off offset:64
	global_load_dwordx4 v[70:73], v[66:67], off offset:512
	s_nop 0
	global_load_dwordx4 v[66:69], v[66:67], off offset:576
	v_lshl_add_u64 v[82:83], v[142:143], 0, v[148:149]
	s_mov_b64 s[16:17], 0x140000
	global_load_dwordx4 v[110:113], v[82:83], off
	global_load_dwordx4 v[106:109], v[82:83], off offset:64
	global_load_dwordx4 v[98:101], v[82:83], off offset:512
	global_load_dwordx4 v[90:93], v[82:83], off offset:576
	v_lshl_add_u64 v[146:147], v[144:145], 0, s[16:17]
	s_mov_b64 s[16:17], 0x160000
	v_lshl_add_u64 v[82:83], v[142:143], 0, v[146:147]
	v_lshl_add_u64 v[144:145], v[144:145], 0, s[16:17]
	global_load_dwordx4 v[102:105], v[82:83], off
	global_load_dwordx4 v[94:97], v[82:83], off offset:64
	global_load_dwordx4 v[86:89], v[82:83], off offset:512
	s_nop 0
	global_load_dwordx4 v[82:85], v[82:83], off offset:576
	v_lshl_add_u64 v[126:127], v[142:143], 0, v[144:145]
	global_load_dwordx4 v[118:121], v[126:127], off
	global_load_dwordx4 v[122:125], v[126:127], off offset:64
	global_load_dwordx4 v[114:117], v[126:127], off offset:512
	s_nop 0
	global_load_dwordx4 v[126:129], v[126:127], off offset:576
	s_mov_b64 s[16:17], s[12:13]
	s_waitcnt vmcnt(0)
	v_pk_fma_f32 v[62:63], v[62:63], 0.5, v[78:79] op_sel_hi:[1,0,1]
	v_lshl_add_u64 v[78:79], s[20:21], 0, v[140:141]
	v_lshl_add_u64 v[78:79], v[78:79], 0, v[138:139]
	v_pk_fma_f32 v[52:53], v[52:53], 0.5, v[72:73] op_sel_hi:[1,0,1]
	v_pk_fma_f32 v[50:51], v[50:51], 0.5, v[70:71] op_sel_hi:[1,0,1]
	global_store_dwordx4 v[78:79], v[50:53], off offset:512
	v_pk_fma_f32 v[36:37], v[36:37], 0.5, v[100:101] op_sel_hi:[1,0,1]
	v_pk_fma_f32 v[34:35], v[34:35], 0.5, v[98:99] op_sel_hi:[1,0,1]
	v_lshl_add_u64 v[50:51], s[20:21], 0, v[148:149]
	v_lshl_add_u64 v[50:51], v[50:51], 0, v[138:139]
	global_store_dwordx4 v[50:51], v[34:37], off offset:512
	v_pk_fma_f32 v[44:45], v[44:45], 0.5, v[68:69] op_sel_hi:[1,0,1]
	v_pk_fma_f32 v[42:43], v[42:43], 0.5, v[66:67] op_sel_hi:[1,0,1]
	v_lshl_add_u64 v[34:35], s[20:21], 0, v[146:147]
	v_pk_fma_f32 v[28:29], v[28:29], 0.5, v[92:93] op_sel_hi:[1,0,1]
	v_pk_fma_f32 v[26:27], v[26:27], 0.5, v[90:91] op_sel_hi:[1,0,1]
	v_lshl_add_u64 v[34:35], v[34:35], 0, v[138:139]
	v_pk_fma_f32 v[20:21], v[20:21], 0.5, v[88:89] op_sel_hi:[1,0,1]
	v_pk_fma_f32 v[18:19], v[18:19], 0.5, v[86:87] op_sel_hi:[1,0,1]
	global_store_dwordx4 v[78:79], v[42:45], off offset:576
	global_store_dwordx4 v[50:51], v[26:29], off offset:576
	global_store_dwordx4 v[34:35], v[18:21], off offset:512
	v_pk_fma_f32 v[44:45], v[56:57], 0.5, v[112:113] op_sel_hi:[1,0,1]
	v_pk_fma_f32 v[42:43], v[54:55], 0.5, v[110:111] op_sel_hi:[1,0,1]
	v_pk_fma_f32 v[28:29], v[40:41], 0.5, v[104:105] op_sel_hi:[1,0,1]
	v_pk_fma_f32 v[26:27], v[38:39], 0.5, v[102:103] op_sel_hi:[1,0,1]
	v_pk_fma_f32 v[16:17], v[16:17], 0.5, v[84:85] op_sel_hi:[1,0,1]
	v_pk_fma_f32 v[14:15], v[14:15], 0.5, v[82:83] op_sel_hi:[1,0,1]
	v_lshl_add_u64 v[18:19], s[20:21], 0, v[144:145]
	v_pk_fma_f32 v[64:65], v[64:65], 0.5, v[80:81] op_sel_hi:[1,0,1]
	v_pk_fma_f32 v[60:61], v[60:61], 0.5, v[76:77] op_sel_hi:[1,0,1]
	v_pk_fma_f32 v[58:59], v[58:59], 0.5, v[74:75] op_sel_hi:[1,0,1]
	global_store_dwordx4 v[50:51], v[42:45], off
	global_store_dwordx4 v[34:35], v[26:29], off
	global_store_dwordx4 v[34:35], v[14:17], off offset:576
	v_pk_fma_f32 v[44:45], v[48:49], 0.5, v[108:109] op_sel_hi:[1,0,1]
	v_pk_fma_f32 v[42:43], v[46:47], 0.5, v[106:107] op_sel_hi:[1,0,1]
	v_pk_fma_f32 v[28:29], v[32:33], 0.5, v[96:97] op_sel_hi:[1,0,1]
	v_pk_fma_f32 v[26:27], v[30:31], 0.5, v[94:95] op_sel_hi:[1,0,1]
	v_pk_fma_f32 v[16:17], v[24:25], 0.5, v[120:121] op_sel_hi:[1,0,1]
	v_pk_fma_f32 v[14:15], v[22:23], 0.5, v[118:119] op_sel_hi:[1,0,1]
	v_lshl_add_u64 v[18:19], v[18:19], 0, v[138:139]
	v_pk_fma_f32 v[12:13], v[12:13], 0.5, v[124:125] op_sel_hi:[1,0,1]
	v_pk_fma_f32 v[10:11], v[10:11], 0.5, v[122:123] op_sel_hi:[1,0,1]
	v_pk_fma_f32 v[8:9], v[8:9], 0.5, v[116:117] op_sel_hi:[1,0,1]
	v_pk_fma_f32 v[6:7], v[6:7], 0.5, v[114:115] op_sel_hi:[1,0,1]
	v_pk_fma_f32 v[4:5], v[4:5], 0.5, v[128:129] op_sel_hi:[1,0,1]
	v_pk_fma_f32 v[2:3], v[2:3], 0.5, v[126:127] op_sel_hi:[1,0,1]
	global_store_dwordx4 v[78:79], v[62:65], off
	global_store_dwordx4 v[78:79], v[58:61], off offset:64
	global_store_dwordx4 v[50:51], v[42:45], off offset:64
	global_store_dwordx4 v[34:35], v[26:29], off offset:64
	global_store_dwordx4 v[18:19], v[14:17], off
	global_store_dwordx4 v[18:19], v[10:13], off offset:64
	global_store_dwordx4 v[18:19], v[6:9], off offset:512
	global_store_dwordx4 v[18:19], v[2:5], off offset:576
	s_cbranch_vccz .LBB0_721
	s_waitcnt vmcnt(0)
	s_cmpk_gt_u32 s4, 0xff
	s_cbranch_scc1 .LBB0_736
	s_barrier

.LBB0_751:
	s_add_u32 s24, s12, 0xfff80080
	s_addc_u32 s25, s13, -1
	s_add_i32 s49, 0, 0x10000
	v_add_u32_e32 v148, s49, v1
	ds_read_b128 v[144:147], v148
	ds_read_b128 v[158:161], v148 offset:1024
	ds_read_b128 v[162:165], v148 offset:2048
	ds_read_b128 v[166:169], v148 offset:3072
	s_cmp_eq_u32 s48, 28
	s_cselect_b32 s27, s19, s25
	s_cselect_b32 s26, s44, s24
	s_cselect_b32 s25, s17, s47
	s_cselect_b32 s24, s45, s46
	v_lshl_add_u64 v[210:211], s[12:13], 0, v[140:141]
	s_add_i32 m0, s39, 0xc000
	ds_read_b128 v[170:173], v156
	ds_read_b128 v[174:177], v156 offset:1024
	ds_read_b128 v[178:181], v156 offset:2048
	ds_read_b128 v[182:185], v156 offset:3072
	ds_read_b128 v[194:197], v156 offset:4096
	ds_read_b128 v[198:201], v156 offset:5120
	ds_read_b128 v[202:205], v156 offset:6144
	ds_read_b128 v[206:209], v156 offset:7168
	global_load_lds_dwordx4 v[210:211], off
	v_lshl_add_u64 v[210:211], s[12:13], 0, v[142:143]
	s_add_i32 m0, s39, 0xe000
	s_nop 0
	global_load_lds_dwordx4 v[210:211], off
	s_waitcnt lgkmcnt(8)
	s_barrier
	s_waitcnt lgkmcnt(0)
	s_setprio 1
	v_mfma_f32_16x16x32_bf16 v[126:129], v[144:147], v[170:173], v[126:129]
	v_mfma_f32_16x16x32_bf16 v[118:121], v[162:165], v[170:173], v[118:121]
	v_mfma_f32_16x16x32_bf16 v[110:113], v[144:147], v[178:181], v[110:113]
	v_mfma_f32_16x16x32_bf16 v[102:105], v[162:165], v[178:181], v[102:105]
	v_mfma_f32_16x16x32_bf16 v[94:97], v[144:147], v[194:197], v[94:97]
	v_mfma_f32_16x16x32_bf16 v[86:89], v[162:165], v[194:197], v[86:89]
	v_mfma_f32_16x16x32_bf16 v[78:81], v[144:147], v[202:205], v[78:81]
	v_mfma_f32_16x16x32_bf16 v[70:73], v[162:165], v[202:205], v[70:73]
	v_mfma_f32_16x16x32_bf16 v[126:129], v[158:161], v[174:177], v[126:129]
	v_mfma_f32_16x16x32_bf16 v[118:121], v[166:169], v[174:177], v[118:121]
	v_mfma_f32_16x16x32_bf16 v[110:113], v[158:161], v[182:185], v[110:113]
	v_mfma_f32_16x16x32_bf16 v[102:105], v[166:169], v[182:185], v[102:105]
	v_mfma_f32_16x16x32_bf16 v[94:97], v[158:161], v[198:201], v[94:97]
	v_mfma_f32_16x16x32_bf16 v[86:89], v[166:169], v[198:201], v[86:89]
	v_mfma_f32_16x16x32_bf16 v[78:81], v[158:161], v[206:209], v[78:81]
	v_mfma_f32_16x16x32_bf16 v[70:73], v[166:169], v[206:209], v[70:73]
	s_setprio 0
	s_barrier
	s_add_i32 s52, 0, 0x14000
	s_add_i32 s49, s49, s34
	v_add_u32_e32 v148, s52, v1
	v_lshl_add_u64 v[220:221], s[24:25], 0, v[134:135]
	s_mov_b32 m0, s49
	ds_read_b128 v[210:213], v148
	ds_read_b128 v[236:239], v148 offset:1024
	ds_read_b128 v[240:243], v148 offset:2048
	ds_read_b128 v[244:247], v148 offset:3072
	global_load_lds_dwordx4 v[220:221], off
	v_lshl_add_u64 v[222:223], s[24:25], 0, v[130:131]
	s_add_i32 m0, s49, 0x2000
	s_nop 0
	global_load_lds_dwordx4 v[222:223], off
	s_barrier
	s_waitcnt lgkmcnt(0)
	s_setprio 1
	v_mfma_f32_16x16x32_bf16 v[122:125], v[210:213], v[170:173], v[122:125]
	v_mfma_f32_16x16x32_bf16 v[114:117], v[240:243], v[170:173], v[114:117]
	v_mfma_f32_16x16x32_bf16 v[106:109], v[210:213], v[178:181], v[106:109]
	v_mfma_f32_16x16x32_bf16 v[98:101], v[240:243], v[178:181], v[98:101]
	v_mfma_f32_16x16x32_bf16 v[90:93], v[210:213], v[194:197], v[90:93]
	v_mfma_f32_16x16x32_bf16 v[82:85], v[240:243], v[194:197], v[82:85]
	v_mfma_f32_16x16x32_bf16 v[74:77], v[210:213], v[202:205], v[74:77]
	v_mfma_f32_16x16x32_bf16 v[66:69], v[240:243], v[202:205], v[66:69]
	v_mfma_f32_16x16x32_bf16 v[122:125], v[236:239], v[174:177], v[122:125]
	v_mfma_f32_16x16x32_bf16 v[114:117], v[244:247], v[174:177], v[114:117]
	v_mfma_f32_16x16x32_bf16 v[106:109], v[236:239], v[182:185], v[106:109]
	v_mfma_f32_16x16x32_bf16 v[98:101], v[244:247], v[182:185], v[98:101]
	v_mfma_f32_16x16x32_bf16 v[90:93], v[236:239], v[198:201], v[90:93]
	v_mfma_f32_16x16x32_bf16 v[82:85], v[244:247], v[198:201], v[82:85]
	v_mfma_f32_16x16x32_bf16 v[74:77], v[236:239], v[206:209], v[74:77]
	v_mfma_f32_16x16x32_bf16 v[66:69], v[244:247], v[206:209], v[66:69]
	s_setprio 0
	s_mov_b32 m0, s39
	v_lshl_add_u64 v[248:249], s[26:27], 0, v[136:137]
	s_barrier
	ds_read_b128 v[170:173], v156 offset:16384
	ds_read_b128 v[174:177], v156 offset:17408
	ds_read_b128 v[178:181], v156 offset:18432
	ds_read_b128 v[182:185], v156 offset:19456
	ds_read_b128 v[194:197], v156 offset:20480
	ds_read_b128 v[198:201], v156 offset:21504
	ds_read_b128 v[202:205], v156 offset:22528
	ds_read_b128 v[206:209], v156 offset:23552
	global_load_lds_dwordx4 v[248:249], off
	v_lshl_add_u64 v[250:251], s[26:27], 0, v[132:133]
	s_mov_b32 m0, s40
	s_nop 0
	global_load_lds_dwordx4 v[250:251], off
	s_barrier
	s_waitcnt lgkmcnt(0)
	s_setprio 1
	v_mfma_f32_16x16x32_bf16 v[62:65], v[144:147], v[170:173], v[62:65]
	v_mfma_f32_16x16x32_bf16 v[54:57], v[162:165], v[170:173], v[54:57]
	v_mfma_f32_16x16x32_bf16 v[46:49], v[144:147], v[178:181], v[46:49]
	v_mfma_f32_16x16x32_bf16 v[38:41], v[162:165], v[178:181], v[38:41]
	v_mfma_f32_16x16x32_bf16 v[30:33], v[144:147], v[194:197], v[30:33]
	v_mfma_f32_16x16x32_bf16 v[22:25], v[162:165], v[194:197], v[22:25]
	v_mfma_f32_16x16x32_bf16 v[14:17], v[144:147], v[202:205], v[14:17]
	v_mfma_f32_16x16x32_bf16 v[6:9], v[162:165], v[202:205], v[6:9]
	v_mfma_f32_16x16x32_bf16 v[62:65], v[158:161], v[174:177], v[62:65]
	v_mfma_f32_16x16x32_bf16 v[54:57], v[166:169], v[174:177], v[54:57]
	v_mfma_f32_16x16x32_bf16 v[46:49], v[158:161], v[182:185], v[46:49]
	v_mfma_f32_16x16x32_bf16 v[38:41], v[166:169], v[182:185], v[38:41]
	v_mfma_f32_16x16x32_bf16 v[30:33], v[158:161], v[198:201], v[30:33]
	v_mfma_f32_16x16x32_bf16 v[22:25], v[166:169], v[198:201], v[22:25]
	v_mfma_f32_16x16x32_bf16 v[14:17], v[158:161], v[206:209], v[14:17]
	v_mfma_f32_16x16x32_bf16 v[6:9], v[166:169], v[206:209], v[6:9]
	s_setprio 0
	s_barrier
	s_add_u32 s50, s24, 0x80000
	s_addc_u32 s51, s25, 0
	s_add_i32 s49, s52, s34
	v_lshl_add_u64 v[144:145], s[50:51], 0, v[134:135]
	s_mov_b32 m0, s49
	s_nop 0
	global_load_lds_dwordx4 v[144:145], off
	v_lshl_add_u64 v[144:145], s[50:51], 0, v[130:131]
	s_add_i32 m0, s49, 0x2000
	s_nop 0
	global_load_lds_dwordx4 v[144:145], off
	s_waitcnt vmcnt(6)
	s_barrier
	s_setprio 1
	v_mfma_f32_16x16x32_bf16 v[58:61], v[210:213], v[170:173], v[58:61]
	v_mfma_f32_16x16x32_bf16 v[50:53], v[240:243], v[170:173], v[50:53]
	v_mfma_f32_16x16x32_bf16 v[42:45], v[210:213], v[178:181], v[42:45]
	v_mfma_f32_16x16x32_bf16 v[34:37], v[240:243], v[178:181], v[34:37]
	v_mfma_f32_16x16x32_bf16 v[26:29], v[210:213], v[194:197], v[26:29]
	v_mfma_f32_16x16x32_bf16 v[18:21], v[240:243], v[194:197], v[18:21]
	v_mfma_f32_16x16x32_bf16 v[10:13], v[210:213], v[202:205], v[10:13]
	v_mfma_f32_16x16x32_bf16 v[2:5], v[240:243], v[202:205], v[2:5]
	v_mfma_f32_16x16x32_bf16 v[58:61], v[236:239], v[174:177], v[58:61]
	v_mfma_f32_16x16x32_bf16 v[50:53], v[244:247], v[174:177], v[50:53]
	v_mfma_f32_16x16x32_bf16 v[42:45], v[236:239], v[182:185], v[42:45]
	v_mfma_f32_16x16x32_bf16 v[34:37], v[244:247], v[182:185], v[34:37]
	v_mfma_f32_16x16x32_bf16 v[26:29], v[236:239], v[198:201], v[26:29]
	v_mfma_f32_16x16x32_bf16 v[18:21], v[244:247], v[198:201], v[18:21]
	v_mfma_f32_16x16x32_bf16 v[10:13], v[236:239], v[206:209], v[10:13]
	v_mfma_f32_16x16x32_bf16 v[2:5], v[244:247], v[206:209], v[2:5]
	s_setprio 0
	s_add_i32 s49, 0, 0x18000
	v_add_u32_e32 v148, s49, v1
	s_barrier
	ds_read_b128 v[144:147], v148
	ds_read_b128 v[158:161], v148 offset:1024
	ds_read_b128 v[162:165], v148 offset:2048
	ds_read_b128 v[166:169], v148 offset:3072
	s_add_u32 s26, s26, 0x80000
	s_addc_u32 s27, s27, 0
	s_mov_b32 m0, s41
	v_lshl_add_u64 v[210:211], s[26:27], 0, v[136:137]
	ds_read_b128 v[170:173], v156 offset:32768
	ds_read_b128 v[174:177], v156 offset:33792
	ds_read_b128 v[178:181], v156 offset:34816
	ds_read_b128 v[182:185], v156 offset:35840
	ds_read_b128 v[194:197], v156 offset:36864
	ds_read_b128 v[198:201], v156 offset:37888
	ds_read_b128 v[202:205], v156 offset:38912
	ds_read_b128 v[206:209], v156 offset:39936
	global_load_lds_dwordx4 v[210:211], off
	v_lshl_add_u64 v[210:211], s[26:27], 0, v[132:133]
	s_mov_b32 m0, s42
	s_nop 0
	global_load_lds_dwordx4 v[210:211], off
	s_waitcnt lgkmcnt(8)
	s_barrier
	s_waitcnt lgkmcnt(0)
	s_setprio 1
	v_mfma_f32_16x16x32_bf16 v[126:129], v[144:147], v[170:173], v[126:129]
	v_mfma_f32_16x16x32_bf16 v[118:121], v[162:165], v[170:173], v[118:121]
	v_mfma_f32_16x16x32_bf16 v[110:113], v[144:147], v[178:181], v[110:113]
	v_mfma_f32_16x16x32_bf16 v[102:105], v[162:165], v[178:181], v[102:105]
	v_mfma_f32_16x16x32_bf16 v[94:97], v[144:147], v[194:197], v[94:97]
	v_mfma_f32_16x16x32_bf16 v[86:89], v[162:165], v[194:197], v[86:89]
	v_mfma_f32_16x16x32_bf16 v[78:81], v[144:147], v[202:205], v[78:81]
	v_mfma_f32_16x16x32_bf16 v[70:73], v[162:165], v[202:205], v[70:73]
	v_mfma_f32_16x16x32_bf16 v[126:129], v[158:161], v[174:177], v[126:129]
	v_mfma_f32_16x16x32_bf16 v[118:121], v[166:169], v[174:177], v[118:121]
	v_mfma_f32_16x16x32_bf16 v[110:113], v[158:161], v[182:185], v[110:113]
	v_mfma_f32_16x16x32_bf16 v[102:105], v[166:169], v[182:185], v[102:105]
	v_mfma_f32_16x16x32_bf16 v[94:97], v[158:161], v[198:201], v[94:97]
	v_mfma_f32_16x16x32_bf16 v[86:89], v[166:169], v[198:201], v[86:89]
	v_mfma_f32_16x16x32_bf16 v[78:81], v[158:161], v[206:209], v[78:81]
	v_mfma_f32_16x16x32_bf16 v[70:73], v[166:169], v[206:209], v[70:73]
	s_setprio 0
	s_barrier
	s_add_i32 s26, 0, 0x1c000
	s_add_i32 s27, s49, s34
	v_add_u32_e32 v148, s26, v1
	v_lshl_add_u64 v[220:221], v[220:221], 0, s[6:7]
	s_mov_b32 m0, s27
	ds_read_b128 v[210:213], v148
	ds_read_b128 v[236:239], v148 offset:1024
	ds_read_b128 v[240:243], v148 offset:2048
	ds_read_b128 v[244:247], v148 offset:3072
	global_load_lds_dwordx4 v[220:221], off
	v_lshl_add_u64 v[220:221], v[222:223], 0, s[6:7]
	s_add_i32 m0, s27, 0x2000
	s_nop 0
	global_load_lds_dwordx4 v[220:221], off
	s_barrier
	s_waitcnt lgkmcnt(0)
	s_setprio 1
	v_mfma_f32_16x16x32_bf16 v[122:125], v[210:213], v[170:173], v[122:125]
	v_mfma_f32_16x16x32_bf16 v[114:117], v[240:243], v[170:173], v[114:117]
	v_mfma_f32_16x16x32_bf16 v[106:109], v[210:213], v[178:181], v[106:109]
	v_mfma_f32_16x16x32_bf16 v[98:101], v[240:243], v[178:181], v[98:101]
	v_mfma_f32_16x16x32_bf16 v[90:93], v[210:213], v[194:197], v[90:93]
	v_mfma_f32_16x16x32_bf16 v[82:85], v[240:243], v[194:197], v[82:85]
	v_mfma_f32_16x16x32_bf16 v[74:77], v[210:213], v[202:205], v[74:77]
	v_mfma_f32_16x16x32_bf16 v[66:69], v[240:243], v[202:205], v[66:69]
	v_mfma_f32_16x16x32_bf16 v[122:125], v[236:239], v[174:177], v[122:125]
	v_mfma_f32_16x16x32_bf16 v[114:117], v[244:247], v[174:177], v[114:117]
	v_mfma_f32_16x16x32_bf16 v[106:109], v[236:239], v[182:185], v[106:109]
	v_mfma_f32_16x16x32_bf16 v[98:101], v[244:247], v[182:185], v[98:101]
	v_mfma_f32_16x16x32_bf16 v[90:93], v[236:239], v[198:201], v[90:93]
	v_mfma_f32_16x16x32_bf16 v[82:85], v[244:247], v[198:201], v[82:85]
	v_mfma_f32_16x16x32_bf16 v[74:77], v[236:239], v[206:209], v[74:77]
	v_mfma_f32_16x16x32_bf16 v[66:69], v[244:247], v[206:209], v[66:69]
	s_setprio 0
	s_mov_b32 m0, s4
	v_lshl_add_u64 v[220:221], v[248:249], 0, s[6:7]
	s_barrier
	ds_read_b128 v[170:173], v156 offset:49152
	ds_read_b128 v[174:177], v156 offset:50176
	ds_read_b128 v[178:181], v156 offset:51200
	ds_read_b128 v[182:185], v156 offset:52224
	ds_read_b128 v[194:197], v156 offset:53248
	ds_read_b128 v[198:201], v156 offset:54272
	ds_read_b128 v[202:205], v156 offset:55296
	ds_read_b128 v[206:209], v156 offset:56320
	global_load_lds_dwordx4 v[220:221], off
	v_lshl_add_u64 v[220:221], v[250:251], 0, s[6:7]
	s_mov_b32 m0, s5
	s_nop 0
	global_load_lds_dwordx4 v[220:221], off
	s_barrier
	s_waitcnt lgkmcnt(0)
	s_setprio 1
	v_mfma_f32_16x16x32_bf16 v[62:65], v[144:147], v[170:173], v[62:65]
	v_mfma_f32_16x16x32_bf16 v[54:57], v[162:165], v[170:173], v[54:57]
	v_mfma_f32_16x16x32_bf16 v[46:49], v[144:147], v[178:181], v[46:49]
	v_mfma_f32_16x16x32_bf16 v[38:41], v[162:165], v[178:181], v[38:41]
	v_mfma_f32_16x16x32_bf16 v[30:33], v[144:147], v[194:197], v[30:33]
	v_mfma_f32_16x16x32_bf16 v[22:25], v[162:165], v[194:197], v[22:25]
	v_mfma_f32_16x16x32_bf16 v[14:17], v[144:147], v[202:205], v[14:17]
	v_mfma_f32_16x16x32_bf16 v[6:9], v[162:165], v[202:205], v[6:9]
	v_mfma_f32_16x16x32_bf16 v[62:65], v[158:161], v[174:177], v[62:65]
	v_mfma_f32_16x16x32_bf16 v[54:57], v[166:169], v[174:177], v[54:57]
	v_mfma_f32_16x16x32_bf16 v[46:49], v[158:161], v[182:185], v[46:49]
	v_mfma_f32_16x16x32_bf16 v[38:41], v[166:169], v[182:185], v[38:41]
	v_mfma_f32_16x16x32_bf16 v[30:33], v[158:161], v[198:201], v[30:33]
	v_mfma_f32_16x16x32_bf16 v[22:25], v[166:169], v[198:201], v[22:25]
	v_mfma_f32_16x16x32_bf16 v[14:17], v[158:161], v[206:209], v[14:17]
	v_mfma_f32_16x16x32_bf16 v[6:9], v[166:169], v[206:209], v[6:9]
	s_setprio 0
	s_barrier
	s_add_u32 s24, s24, 0x80080
	s_addc_u32 s25, s25, 0
	s_add_i32 s26, s26, s34
	v_lshl_add_u64 v[144:145], s[24:25], 0, v[134:135]
	s_mov_b32 m0, s26
	s_nop 0
	global_load_lds_dwordx4 v[144:145], off
	v_lshl_add_u64 v[144:145], s[24:25], 0, v[130:131]
	s_add_i32 m0, s26, 0x2000
	s_nop 0
	global_load_lds_dwordx4 v[144:145], off
	s_waitcnt vmcnt(6)
	s_barrier
	s_setprio 1
	v_mfma_f32_16x16x32_bf16 v[58:61], v[210:213], v[170:173], v[58:61]
	v_mfma_f32_16x16x32_bf16 v[50:53], v[240:243], v[170:173], v[50:53]
	v_mfma_f32_16x16x32_bf16 v[42:45], v[210:213], v[178:181], v[42:45]
	v_mfma_f32_16x16x32_bf16 v[34:37], v[240:243], v[178:181], v[34:37]
	v_mfma_f32_16x16x32_bf16 v[26:29], v[210:213], v[194:197], v[26:29]
	v_mfma_f32_16x16x32_bf16 v[18:21], v[240:243], v[194:197], v[18:21]
	v_mfma_f32_16x16x32_bf16 v[10:13], v[210:213], v[202:205], v[10:13]
	v_mfma_f32_16x16x32_bf16 v[2:5], v[240:243], v[202:205], v[2:5]
	v_mfma_f32_16x16x32_bf16 v[58:61], v[236:239], v[174:177], v[58:61]
	v_mfma_f32_16x16x32_bf16 v[50:53], v[244:247], v[174:177], v[50:53]
	v_mfma_f32_16x16x32_bf16 v[42:45], v[236:239], v[182:185], v[42:45]
	v_mfma_f32_16x16x32_bf16 v[34:37], v[244:247], v[182:185], v[34:37]
	v_mfma_f32_16x16x32_bf16 v[26:29], v[236:239], v[198:201], v[26:29]
	v_mfma_f32_16x16x32_bf16 v[18:21], v[244:247], v[198:201], v[18:21]
	v_mfma_f32_16x16x32_bf16 v[10:13], v[236:239], v[206:209], v[10:13]
	v_mfma_f32_16x16x32_bf16 v[2:5], v[244:247], v[206:209], v[2:5]
	s_setprio 0
	s_add_i32 s48, s48, 2
	s_add_u32 s12, s12, 0x100
	s_addc_u32 s13, s13, 0
	s_add_u32 s46, s46, 0x100
	s_addc_u32 s47, s47, 0
	s_cmp_gt_u32 s48, 29
	s_barrier
	s_cbranch_scc0 .LBB0_751
	s_nop 0
	s_nop 0
	s_nop 0
	s_nop 0
	s_nop 0
	s_nop 0
	ds_read_b32 v160, v149
	ds_read_b32 v161, v149 offset:64
	ds_read_b32 v162, v149 offset:128
	ds_read_b32 v163, v150
	ds_read_b32 v164, v151
	ds_read_b32 v165, v152
	ds_read_b32 v166, v153
	ds_read_b32 v167, v154
	s_lshl_b32 s24, s29, 8
	s_cmp_lg_u32 s29, s30
	v_add_u32_e32 v144, s24, v138
	s_cselect_b64 s[26:27], -1, 0
	s_mov_b64 s[12:13], -1
	s_and_b64 vcc, exec, s[26:27]
	v_ashrrev_i32_e32 v145, 31, v144
	s_cbranch_vccz .LBB0_754
	v_lshl_add_u64 v[146:147], v[144:145], 2, s[14:15]
	global_load_dword v146, v[146:147], off
	s_mov_b64 s[12:13], 0
	s_waitcnt vmcnt(0)
	v_fmamk_f32 v146, v146, 0x3a000000, v215
	v_mul_f32_e32 v147, 0x4b800000, v146
	v_cmp_gt_f32_e32 vcc, s65, v146
	s_nop 1
	v_cndmask_b32_e32 v146, v146, v147, vcc
	v_rsq_f32_e32 v146, v146
	s_nop 0
	v_mul_f32_e32 v147, 0x45800000, v146
	v_cndmask_b32_e32 v148, v146, v147, vcc
